# G1 and G3 epilogue flat loads/stores converted to global
# speedup vs baseline: 1.0016x; 1.0016x over previous
; __device__ __forceinline__ float bperm_f(int src_lane, float v) { return __builtin_bit_cast(float, __builtin_amdgcn_ds_bpermute(src_lane << 2, __builtin_bit_cast(int, v))); }
;     __device__ __forceinline__ void operator()(Acc& acc, const Unit& u, int wr, int wc, int fr, int fq) const {
;         const int b = u.pm / UPU, j = u.pm % UPU;
;         const int tbase = 252 * j + 126 * wr - 2 + fr;
;         const int ch0 = 128 * u.pn + 32 * wc + 8 * fq;
;         float chain = 0.f;
;         { const int ln = (fq << 4) | fr; f32x4 pq[8];
; #pragma unroll
;           for (int q = 0; q < 8; ++q) { const int t = tbase + 16 * q; const bool ok = (t >= 0) && (t < SEQ); pq[q] = *(const f32x4*)(ssq + (size_t)(b * SEQ + (ok ? t : 0)) * 16 + 4 * fq); }
; #pragma unroll
;           for (int q = 0; q < 8; ++q) {
;             const int t = tbase + 16 * q; const bool ok = (t >= 0) && (t < SEQ);
;             float sq = (pq[q][0] + pq[q][1]) + (pq[q][2] + pq[q][3]); sq += bperm_f(ln ^ 16, sq); sq += bperm_f(ln ^ 32, sq);
;             const float rs = rsqrtf(sq * (1.0f / DM) + EPS);
; #pragma unroll
;             for (int bj = 0; bj < 2; ++bj)
; #pragma unroll
;                 for (int n = 0; n < 2; ++n)
; #pragma unroll
;                     for (int i = 0; i < 4; ++i) { const float v = acc[q >> 2][bj][q & 3][n][i]; acc[q >> 2][bj][q & 3][n][i] = ok ? v * rs : 0.f; }
.LBB0_43:
	s_mul_hi_i32 s21, s20, 0x3e0f83e1
	s_lshr_b32 s27, s21, 31
	s_ashr_i32 s21, s21, 3
	s_add_i32 s21, s21, s27
	s_mul_i32 s27, s21, 33
	s_sub_i32 s20, s20, s27
	s_mulk_i32 s20, 0xfc
	v_add_u32_e32 v198, s20, v194
	v_add_u32_e32 v223, 16, v198
	v_cmp_gt_u32_e64 s[56:57], s97, v198
	v_cmp_gt_u32_e64 s[52:53], s97, v223
	s_lshl_b32 s20, s21, 13
	v_cndmask_b32_e64 v132, 0, v198, s[56:57]
	v_cndmask_b32_e64 v136, 0, v223, s[52:53]
	v_add_u32_e32 v132, s20, v132
	v_add_u32_e32 v136, s20, v136
	v_ashrrev_i32_e32 v133, 31, v132
	v_ashrrev_i32_e32 v137, 31, v136
	v_lshlrev_b64 v[132:133], 6, v[132:133]
	v_lshlrev_b64 v[136:137], 6, v[136:137]
	v_lshl_add_u64 v[132:133], v[146:147], 0, v[132:133]
	v_lshl_add_u64 v[136:137], v[146:147], 0, v[136:137]
	global_load_dwordx4 v[132:135], v[132:133], off
	v_add_u32_e32 v227, 32, v198
	global_load_dwordx4 v[136:139], v[136:137], off
	v_add_u32_e32 v226, 48, v198
	v_cmp_gt_u32_e64 s[54:55], s97, v227
	v_add_u32_e32 v225, 64, v198
	v_cmp_gt_u32_e64 s[50:51], s97, v226
	v_cndmask_b32_e64 v152, 0, v227, s[54:55]
	v_cmp_gt_u32_e64 s[48:49], s97, v225
	v_cndmask_b32_e64 v153, 0, v226, s[50:51]
	v_add_u32_e32 v152, s20, v152
	v_cndmask_b32_e64 v155, 0, v225, s[48:49]
	v_add_u32_e32 v154, s20, v153
	v_ashrrev_i32_e32 v153, 31, v152
	v_add_u32_e32 v156, s20, v155
	v_ashrrev_i32_e32 v155, 31, v154
	v_lshlrev_b64 v[152:153], 6, v[152:153]
	v_lshlrev_b64 v[154:155], 6, v[154:155]
	v_add_u32_e32 v224, 0x50, v198
	v_cmp_gt_u32_e64 s[46:47], s97, v224
	s_mov_b32 s44, 0x358637bd
	v_add_u32_e32 v222, 0x60, v198
	v_add_u32_e32 v199, 0x70, v198
	v_cndmask_b32_e64 v157, 0, v224, s[46:47]
	v_mov_b64_e32 v[188:189], s[44:45]
	v_cmp_gt_u32_e64 s[44:45], s97, v222
	v_cmp_gt_u32_e32 vcc, s97, v199
	v_add_u32_e32 v158, s20, v157
	v_ashrrev_i32_e32 v157, 31, v156
	v_cndmask_b32_e64 v159, 0, v222, s[44:45]
	v_cndmask_b32_e32 v161, 0, v199, vcc
	v_lshlrev_b64 v[156:157], 6, v[156:157]
	s_mov_b32 s90, 0x3a800000
	v_add_u32_e32 v160, s20, v159
	v_add_u32_e32 v162, s20, v161
	v_ashrrev_i32_e32 v159, 31, v158
	v_ashrrev_i32_e32 v161, 31, v160
	v_ashrrev_i32_e32 v163, 31, v162
	v_lshlrev_b64 v[158:159], 6, v[158:159]
	v_lshlrev_b64 v[160:161], 6, v[160:161]
	v_lshlrev_b64 v[162:163], 6, v[162:163]
	s_waitcnt vmcnt(0) lgkmcnt(0)
	v_add_f32_e32 v174, v133, v132
	v_add_f32_e32 v175, v134, v135
	v_add_f32_e32 v133, v174, v175
	v_add_f32_e32 v174, v137, v136
	v_add_f32_e32 v175, v138, v139
	v_add_f32_e32 v132, v174, v175
	v_lshl_add_u64 v[136:137], v[146:147], 0, v[152:153]
	v_lshl_add_u64 v[138:139], v[146:147], 0, v[154:155]
	global_load_dwordx4 v[190:193], v[136:137], off
	global_load_dwordx4 v[228:231], v[138:139], off
	ds_bpermute_b32 v135, v195, v133
	ds_bpermute_b32 v134, v195, v132
	v_lshl_add_u64 v[136:137], v[146:147], 0, v[156:157]
	v_lshl_add_u64 v[138:139], v[146:147], 0, v[158:159]
	v_lshl_add_u64 v[152:153], v[146:147], 0, v[160:161]
	v_lshl_add_u64 v[154:155], v[146:147], 0, v[162:163]
	s_waitcnt lgkmcnt(0)
	v_pk_add_f32 v[132:133], v[132:133], v[134:135]
	ds_bpermute_b32 v135, v196, v133
	ds_bpermute_b32 v134, v196, v132
	s_waitcnt lgkmcnt(0)
	v_pk_add_f32 v[132:133], v[132:133], v[134:135]
	s_nop 0
	v_pk_fma_f32 v[156:157], v[132:133], s[90:91], v[188:189] op_sel_hi:[1,0,0]
	s_nop 0
	v_mul_f32_e32 v132, 0x4b800000, v157
	v_cmp_gt_f32_e64 s[58:59], s29, v157
	s_nop 1
	v_cndmask_b32_e64 v132, v157, v132, s[58:59]
	v_rsq_f32_e32 v157, v132
	global_load_dwordx4 v[232:235], v[136:137], off
	global_load_dwordx4 v[236:239], v[138:139], off
	s_nop 0
	global_load_dwordx4 v[136:139], v[152:153], off
	global_load_dwordx4 v[132:135], v[154:155], off
	v_mul_f32_e32 v152, 0x45800000, v157
	v_cndmask_b32_e64 v153, v157, v152, s[58:59]
	v_mul_f32_e32 v157, v122, v153
	v_cndmask_b32_e64 v153, 0, v153, s[56:57]
	v_mul_legacy_f32 v122, v126, v153
	v_mul_legacy_f32 v152, v108, v153
	v_mul_f32_e32 v108, v109, v153
	v_mul_f32_e32 v109, 0x4b800000, v156
	v_cmp_gt_f32_e64 s[58:59], s29, v156
	v_cndmask_b32_e64 v109, v156, v109, s[58:59]
	v_rsq_f32_e32 v109, v109
	v_mul_legacy_f32 v182, v128, v153
	v_cndmask_b32_e64 v128, 0, v108, s[56:57]
	v_mul_legacy_f32 v160, v130, v153
	v_mul_legacy_f32 v130, v124, v153
	v_mul_legacy_f32 v124, v110, v153
	v_mul_legacy_f32 v110, v111, v153
	v_mul_f32_e32 v108, 0x45800000, v109
	v_cndmask_b32_e64 v108, v109, v108, s[58:59]
	v_cndmask_b32_e64 v108, 0, v108, s[52:53]
	v_mul_legacy_f32 v187, v116, v108
	v_mul_legacy_f32 v181, v117, v108
	v_mul_legacy_f32 v175, v118, v108
	v_cndmask_b32_e64 v162, 0, v157, s[56:57]
	v_mul_legacy_f32 v157, v119, v108
	v_mul_legacy_f32 v119, v112, v108
	v_mul_legacy_f32 v117, v113, v108
	v_mul_legacy_f32 v186, v104, v108
	v_mul_legacy_f32 v113, v114, v108
	v_mul_f32_e32 v109, v115, v108
	v_mul_legacy_f32 v180, v105, v108
	v_mul_legacy_f32 v174, v106, v108
	v_mul_legacy_f32 v156, v107, v108
	v_mul_legacy_f32 v118, v92, v108
	s_waitcnt vmcnt(0)
	v_add_f32_e32 v114, v191, v190
	v_add_f32_e32 v115, v192, v193
	v_add_f32_e32 v105, v114, v115
	v_add_f32_e32 v114, v229, v228
	v_add_f32_e32 v115, v230, v231
	v_add_f32_e32 v104, v114, v115
	ds_bpermute_b32 v115, v195, v105
	ds_bpermute_b32 v114, v195, v104
	v_mul_legacy_f32 v116, v93, v108
	s_waitcnt lgkmcnt(0)
	v_pk_add_f32 v[104:105], v[104:105], v[114:115]
	ds_bpermute_b32 v107, v196, v105
	ds_bpermute_b32 v106, v196, v104
	v_mul_f32_e32 v155, v120, v153
	v_mul_legacy_f32 v178, v121, v153
	s_waitcnt lgkmcnt(0)
; __device__ __forceinline__ float bperm_f(int src_lane, float v) { return __builtin_bit_cast(float, __builtin_amdgcn_ds_bpermute(src_lane << 2, __builtin_bit_cast(int, v))); }
;     __device__ __forceinline__ void operator()(Acc& acc, const Unit& u, int wr, int wc, int fr, int fq) const {
;     ...
;           for (int q = 0; q < 8; ++q) {
;             const int t = tbase + 16 * q; const bool ok = (t >= 0) && (t < SEQ);
;             float sq = (pq[q][0] + pq[q][1]) + (pq[q][2] + pq[q][3]); sq += bperm_f(ln ^ 16, sq); sq += bperm_f(ln ^ 32, sq);
;             const float rs = rsqrtf(sq * (1.0f / DM) + EPS);
; #pragma unroll
;             for (int bj = 0; bj < 2; ++bj)
; #pragma unroll
;                 for (int n = 0; n < 2; ++n)
; #pragma unroll
;                     for (int i = 0; i < 4; ++i) { const float v = acc[q >> 2][bj][q & 3][n][i]; acc[q >> 2][bj][q & 3][n][i] = ok ? v * rs : 0.f; }
	v_pk_add_f32 v[92:93], v[104:105], v[106:107]
	v_mul_legacy_f32 v176, v129, v153
	v_pk_fma_f32 v[92:93], v[92:93], s[90:91], v[188:189] op_sel_hi:[1,0,0]
	v_mul_legacy_f32 v154, v131, v153
	v_mul_legacy_f32 v126, v125, v153
	v_mul_legacy_f32 v120, v127, v153
	v_cndmask_b32_e64 v184, 0, v155, s[56:57]
	v_mul_legacy_f32 v158, v123, v153
	v_mul_f32_e32 v104, 0x4b800000, v93
	v_cmp_gt_f32_e64 s[56:57], s29, v93
	v_mul_legacy_f32 v112, v94, v108
	v_cndmask_b32_e64 v93, v93, v104, s[56:57]
	v_rsq_f32_e32 v93, v93
	v_mul_legacy_f32 v108, v95, v108
	v_cndmask_b32_e64 v109, 0, v109, s[52:53]
	v_mul_f32_e32 v94, 0x45800000, v93
	v_cndmask_b32_e64 v111, v93, v94, s[56:57]
	v_mul_f32_e32 v93, v100, v111
	v_cndmask_b32_e64 v111, 0, v111, s[54:55]
	v_mul_legacy_f32 v100, v76, v111
	v_mul_f32_e32 v76, v77, v111
	v_mul_f32_e32 v77, 0x4b800000, v92
	v_cmp_gt_f32_e64 s[52:53], s29, v92
	v_cndmask_b32_e64 v115, 0, v93, s[54:55]
	v_cndmask_b32_e64 v77, v92, v77, s[52:53]
	v_mul_legacy_f32 v107, v101, v111
	v_rsq_f32_e32 v77, v77
	v_mul_legacy_f32 v105, v102, v111
	v_mul_legacy_f32 v103, v103, v111
	v_mul_f32_e32 v93, v96, v111
	v_cndmask_b32_e64 v96, 0, v76, s[54:55]
	v_mul_legacy_f32 v94, v78, v111
	v_mul_legacy_f32 v92, v79, v111
	v_mul_f32_e32 v76, 0x45800000, v77
	v_cndmask_b32_e64 v101, 0, v93, s[54:55]
	v_cndmask_b32_e64 v76, v77, v76, s[52:53]
	v_mul_legacy_f32 v97, v97, v111
	v_mul_legacy_f32 v114, v88, v111
	v_mul_legacy_f32 v95, v98, v111
	v_mul_f32_e32 v93, v99, v111
	v_mul_legacy_f32 v106, v89, v111
	v_cndmask_b32_e64 v76, 0, v76, s[50:51]
	v_mul_legacy_f32 v99, v84, v76
	v_mul_legacy_f32 v104, v90, v111
	v_mul_f32_e32 v88, v91, v111
	v_mul_legacy_f32 v91, v85, v76
	v_mul_legacy_f32 v89, v86, v76
	v_mul_legacy_f32 v87, v87, v76
	v_mul_legacy_f32 v85, v80, v76
	v_mul_legacy_f32 v81, v81, v76
	v_mul_legacy_f32 v98, v72, v76
	v_mul_legacy_f32 v79, v82, v76
	v_mul_f32_e32 v77, v83, v76
	v_mul_legacy_f32 v90, v73, v76
	v_add_f32_e32 v82, v233, v232
	v_add_f32_e32 v83, v234, v235
	v_add_f32_e32 v73, v82, v83
	v_add_f32_e32 v82, v237, v236
	v_add_f32_e32 v83, v238, v239
	v_add_f32_e32 v72, v82, v83
	ds_bpermute_b32 v83, v195, v73
	ds_bpermute_b32 v82, v195, v72
	v_cndmask_b32_e64 v102, 0, v88, s[54:55]
	v_mul_legacy_f32 v88, v74, v76
	s_waitcnt lgkmcnt(0)
	v_pk_add_f32 v[72:73], v[72:73], v[82:83]
	v_mul_legacy_f32 v86, v75, v76
	ds_bpermute_b32 v75, v196, v73
	ds_bpermute_b32 v74, v196, v72
	v_mul_legacy_f32 v84, v68, v76
	v_mul_legacy_f32 v80, v69, v76
	s_waitcnt lgkmcnt(0)
	v_pk_add_f32 v[68:69], v[72:73], v[74:75]
	v_mul_f32_e32 v70, v70, v76
	v_pk_fma_f32 v[82:83], v[68:69], s[90:91], v[188:189] op_sel_hi:[1,0,0]
	v_mul_f32_e32 v68, 0x4b800000, v83
	v_cmp_gt_f32_e64 s[52:53], s29, v83
	v_mul_legacy_f32 v76, v71, v76
	v_cndmask_b32_e64 v77, 0, v77, s[50:51]
	v_cndmask_b32_e64 v68, v83, v68, s[52:53]
	v_rsq_f32_e32 v68, v68
	v_cndmask_b32_e64 v78, 0, v70, s[50:51]
	v_cmp_gt_f32_e64 s[50:51], s29, v82
	v_cndmask_b32_e64 v93, 0, v93, s[54:55]
	v_mul_f32_e32 v69, 0x45800000, v68
	v_cndmask_b32_e64 v83, v68, v69, s[52:53]
	v_cndmask_b32_e64 v83, 0, v83, s[48:49]
	v_mul_legacy_f32 v68, v44, v83
	v_mul_f32_e32 v44, v45, v83
	v_mul_f32_e32 v45, 0x4b800000, v82
	v_cndmask_b32_e64 v45, v82, v45, s[50:51]
	v_mul_legacy_f32 v191, v64, v83
	v_rsq_f32_e32 v45, v45
	v_mul_legacy_f32 v75, v65, v83
	v_mul_legacy_f32 v69, v60, v83
	v_mul_legacy_f32 v73, v66, v83
	v_mul_f32_e32 v64, v67, v83
	v_mul_legacy_f32 v67, v61, v83
	v_cndmask_b32_e64 v66, 0, v44, s[48:49]
	v_cndmask_b32_e64 v71, 0, v64, s[48:49]
	v_mul_legacy_f32 v65, v62, v83
	v_mul_legacy_f32 v64, v46, v83
	v_mul_legacy_f32 v61, v63, v83
	v_mul_legacy_f32 v60, v47, v83
	v_mul_f32_e32 v44, 0x45800000, v45
	v_cndmask_b32_e64 v44, v45, v44, s[50:51]
	v_mul_legacy_f32 v190, v56, v83
	v_mul_legacy_f32 v74, v57, v83
	v_cndmask_b32_e64 v44, 0, v44, s[46:47]
	v_mul_legacy_f32 v193, v52, v44
	v_mul_legacy_f32 v72, v58, v83
	v_mul_f32_e32 v56, v59, v83
	v_mul_legacy_f32 v59, v53, v44
	v_mul_legacy_f32 v57, v54, v44
	v_mul_legacy_f32 v55, v55, v44
	v_mul_legacy_f32 v53, v48, v44
	v_mul_legacy_f32 v49, v49, v44
	v_mul_legacy_f32 v192, v40, v44
	v_mul_legacy_f32 v47, v50, v44
	v_mul_f32_e32 v45, v51, v44
	v_mul_legacy_f32 v58, v41, v44
	v_add_f32_e32 v50, v137, v136
	v_add_f32_e32 v51, v138, v139
	v_add_f32_e32 v41, v50, v51
	v_add_f32_e32 v50, v133, v132
	v_add_f32_e32 v51, v134, v135
	v_add_f32_e32 v40, v50, v51
	ds_bpermute_b32 v51, v195, v41
	ds_bpermute_b32 v50, v195, v40
	v_cndmask_b32_e64 v70, 0, v56, s[48:49]
	v_mul_legacy_f32 v56, v42, v44
	s_waitcnt lgkmcnt(0)
	v_pk_add_f32 v[40:41], v[40:41], v[50:51]
	v_mul_legacy_f32 v54, v43, v44
	ds_bpermute_b32 v43, v196, v41
	ds_bpermute_b32 v42, v196, v40
	v_mul_legacy_f32 v52, v28, v44
	v_mul_legacy_f32 v48, v29, v44
	s_waitcnt lgkmcnt(0)
; __device__ __forceinline__ float sigmoidf_(float x) { return __builtin_amdgcn_rcpf(1.0f + __expf(-x)); }
; template <int N> __device__ __forceinline__ float dpp_ror(float v) { return __builtin_bit_cast(float, __builtin_amdgcn_update_dpp(0, __builtin_bit_cast(int, v), 0x120 + N, 0xf, 0xf, false)); }
;     __device__ __forceinline__ void operator()(Acc& acc, const Unit& u, int wr, int wc, int fr, int fq) const {
;     ...
;           for (int q = 0; q < 8; ++q) {
;             const int t = tbase + 16 * q; const bool ok = (t >= 0) && (t < SEQ);
;             float sq = (pq[q][0] + pq[q][1]) + (pq[q][2] + pq[q][3]); sq += bperm_f(ln ^ 16, sq); sq += bperm_f(ln ^ 32, sq);
;             const float rs = rsqrtf(sq * (1.0f / DM) + EPS);
; #pragma unroll
;             for (int bj = 0; bj < 2; ++bj)
; #pragma unroll
;                 for (int n = 0; n < 2; ++n)
; #pragma unroll
;                     for (int i = 0; i < 4; ++i) { const float v = acc[q >> 2][bj][q & 3][n][i]; acc[q >> 2][bj][q & 3][n][i] = ok ? v * rs : 0.f; }
;     ...
;             for (int i = 0; i < 4; ++i) {
;                 const int cg_ = ch0 + 4 * n + i, cv_ = DFF + cg_;
;                 const float g0 = cw[cg_], g1 = cw[NUP + cg_], g2 = cw[2 * NUP + cg_], gb = cb[cg_];
;                 const float v0 = cw[cv_], v1 = cw[NUP + cv_], v2 = cw[2 * NUP + cv_], vb = cb[cv_];
;                 float pg1 = 0.f, pg2 = 0.f, pv1 = 0.f, pv2 = 0.f;
; #pragma unroll
;                 for (int q = 0; q < 8; ++q) {
;                     float cgv = acc[q >> 2][0][q & 3][n][i], cvv = acc[q >> 2][1][q & 3][n][i];
;                     asm volatile("" : "+v"(cgv), "+v"(cvv) : "v"(chain));
;                     const float tg1 = dpp_ror<1>(cgv), tg2 = dpp_ror<2>(cgv), tv1 = dpp_ror<1>(cvv), tv2 = dpp_ror<2>(cvv);
;                     const float sg1 = fr >= 1 ? tg1 : pg1, sg2 = fr >= 2 ? tg2 : pg2, sv1 = fr >= 1 ? tv1 : pv1, sv2 = fr >= 2 ? tv2 : pv2;
;                     const float gg = gb + g0 * sg2 + g1 * sg1 + g2 * cgv;
;                     const float vv = vb + v0 * sv2 + v1 * sv1 + v2 * cvv;
;                     chain = gg * sigmoidf_(gg) * vv; acc[q >> 2][0][q & 3][n][i] = chain;
;                     pg1 = tg1; pg2 = tg2; pv1 = tv1; pv2 = tv2;
;                 }
	v_pk_add_f32 v[28:29], v[40:41], v[42:43]
	v_pk_fma_f32 v[28:29], v[28:29], s[90:91], v[188:189] op_sel_hi:[1,0,0]
	v_mul_legacy_f32 v46, v30, v44
	v_mul_f32_e32 v40, 0x4b800000, v29
	v_cmp_gt_f32_e64 s[48:49], s29, v29
	v_mul_legacy_f32 v44, v31, v44
	v_cndmask_b32_e64 v29, v29, v40, s[48:49]
	v_rsq_f32_e32 v29, v29
	v_cndmask_b32_e64 v45, 0, v45, s[46:47]
	v_cmp_gt_f32_e64 s[46:47], s29, v28
	v_mul_f32_e32 v30, 0x45800000, v29
	v_cndmask_b32_e64 v40, v29, v30, s[48:49]
	v_mul_f32_e32 v29, v36, v40
	v_cndmask_b32_e64 v40, 0, v40, s[44:45]
	v_mul_legacy_f32 v36, v12, v40
	v_mul_f32_e32 v12, v13, v40
	v_mul_f32_e32 v13, 0x4b800000, v28
	v_cndmask_b32_e64 v133, 0, v29, s[44:45]
	v_cndmask_b32_e64 v13, v28, v13, s[46:47]
	v_mul_legacy_f32 v63, v37, v40
	v_rsq_f32_e32 v13, v13
	v_mul_legacy_f32 v43, v38, v40
	v_mul_legacy_f32 v39, v39, v40
	v_mul_f32_e32 v29, v32, v40
	v_cndmask_b32_e64 v32, 0, v12, s[44:45]
	v_mul_legacy_f32 v30, v14, v40
	v_mul_legacy_f32 v28, v15, v40
	v_mul_f32_e32 v12, 0x45800000, v13
	v_cndmask_b32_e64 v12, v13, v12, s[46:47]
	v_cndmask_b32_e32 v12, 0, v12, vcc
	v_mul_legacy_f32 v135, v20, v12
	v_mul_legacy_f32 v83, v21, v12
	v_cndmask_b32_e64 v37, 0, v29, s[44:45]
	v_mul_legacy_f32 v51, v22, v12
	v_mul_legacy_f32 v33, v33, v40
	v_mul_legacy_f32 v132, v24, v40
	v_mul_legacy_f32 v41, v23, v12
	v_mul_legacy_f32 v31, v34, v40
	v_mul_f32_e32 v29, v35, v40
	v_mul_legacy_f32 v62, v25, v40
	v_mul_legacy_f32 v35, v16, v12
	v_mul_legacy_f32 v134, v8, v12
	v_mul_legacy_f32 v34, v4, v12
	v_mul_legacy_f32 v42, v26, v40
	v_mul_f32_e32 v24, v27, v40
	v_mul_legacy_f32 v27, v17, v12
	v_mul_legacy_f32 v82, v9, v12
	v_mul_legacy_f32 v26, v5, v12
	v_mul_legacy_f32 v15, v18, v12
	v_mul_legacy_f32 v50, v10, v12
	v_mul_legacy_f32 v14, v6, v12
	v_cndmask_b32_e64 v29, 0, v29, s[44:45]
	v_cndmask_b32_e64 v38, 0, v24, s[44:45]
	v_mul_legacy_f32 v13, v19, v12
	v_mul_legacy_f32 v40, v11, v12
	v_mul_legacy_f32 v12, v7, v12
	v_lshl_or_b32 v4, s34, 7, v2
	v_ashrrev_i32_e32 v5, 31, v4
	v_lshlrev_b64 v[16:17], 2, v[4:5]
	v_lshl_add_u64 v[6:7], s[36:37], 0, v[16:17]
	s_movk_i32 s21, 0x5000
	v_add_co_u32_e32 v8, vcc, s21, v6
	s_mov_b32 s21, 0xb000
	s_nop 0
	v_addc_co_u32_e32 v9, vcc, 0, v7, vcc
	v_add_co_u32_e32 v10, vcc, s21, v6
	v_lshl_add_u64 v[16:17], s[60:61], 0, v[16:17]
	s_nop 0
	v_addc_co_u32_e32 v11, vcc, 0, v7, vcc
	global_load_dword v139, v[6:7], off
	global_load_dword v137, v[8:9], off offset:2048
	global_load_dword v136, v[10:11], off
	global_load_dword v189, v[16:17], off
	v_add_co_u32_e32 v18, vcc, s97, v6
	s_mov_b32 s21, 0xd000
	s_nop 0
	v_addc_co_u32_e32 v19, vcc, 0, v7, vcc
	v_add_co_u32_e32 v22, vcc, s80, v6
	global_load_dword v138, v[18:19], off offset:3072
	s_nop 0
	v_addc_co_u32_e32 v23, vcc, 0, v7, vcc
	v_add_co_u32_e32 v20, vcc, s97, v16
	s_nop 0
	s_nop 0
	v_addc_co_u32_e32 v21, vcc, 0, v17, vcc
	v_add_co_u32_e32 v24, vcc, s21, v6
	global_load_dword v188, v[20:21], off offset:3072
	s_nop 0
	v_addc_co_u32_e32 v25, vcc, 0, v7, vcc
	global_load_dword v229, v[22:23], off offset:1024
	global_load_dword v228, v[24:25], off offset:3072
	global_load_dword v232, v[6:7], off offset:4
	global_load_dword v233, v[8:9], off offset:2052
	global_load_dword v234, v[10:11], off offset:4
	global_load_dword v235, v[16:17], off offset:4
	global_load_dword v236, v[20:21], off offset:3076
	global_load_dword v237, v[18:19], off offset:3076
	global_load_dword v238, v[22:23], off offset:1028
	global_load_dword v239, v[24:25], off offset:3076
	s_nop 0
	v_mov_b32_dpp v111, v182 row_ror:1 row_mask:0xf bank_mask:0xf
	v_mov_b32_dpp v121, v182 row_ror:2 row_mask:0xf bank_mask:0xf
	v_cndmask_b32_e64 v183, v111, 0, s[38:39]
	v_cndmask_b32_e64 v155, 0, v121, s[40:41]
	v_mov_b32_dpp v123, v184 row_ror:1 row_mask:0xf bank_mask:0xf
	v_mov_b32_dpp v125, v184 row_ror:2 row_mask:0xf bank_mask:0xf
	v_cndmask_b32_e64 v185, v123, 0, s[38:39]
	v_cndmask_b32_e64 v159, 0, v125, s[40:41]
	s_waitcnt vmcnt(13)
	v_pk_mul_f32 v[182:183], v[136:137], v[182:183]
	s_waitcnt vmcnt(12)
	v_fma_f32 v155, v139, v155, v189
	v_add_f32_e32 v155, v183, v155
	v_add_f32_e32 v155, v182, v155
	v_mul_f32_e32 v161, 0xbfb8aa3b, v155
	v_exp_f32_e32 v161, v161
	v_mov_b32_e32 v183, v136
	v_add_f32_e32 v136, 1.0, v161
	v_rcp_f32_e32 v161, v136
	s_waitcnt vmcnt(10)
	v_fma_f32 v159, v138, v159, v188
	v_mul_f32_e32 v155, v155, v161
	s_waitcnt vmcnt(9)
	v_mov_b32_e32 v136, v229
	s_waitcnt vmcnt(8)
; __device__ __forceinline__ float sigmoidf_(float x) { return __builtin_amdgcn_rcpf(1.0f + __expf(-x)); }
; template <int N> __device__ __forceinline__ float dpp_ror(float v) { return __builtin_bit_cast(float, __builtin_amdgcn_update_dpp(0, __builtin_bit_cast(int, v), 0x120 + N, 0xf, 0xf, false)); }
;     __device__ __forceinline__ void operator()(Acc& acc, const Unit& u, int wr, int wc, int fr, int fq) const {
;     ...
;                 for (int q = 0; q < 8; ++q) {
;                     float cgv = acc[q >> 2][0][q & 3][n][i], cvv = acc[q >> 2][1][q & 3][n][i];
;                     asm volatile("" : "+v"(cgv), "+v"(cvv) : "v"(chain));
;                     const float tg1 = dpp_ror<1>(cgv), tg2 = dpp_ror<2>(cgv), tv1 = dpp_ror<1>(cvv), tv2 = dpp_ror<2>(cvv);
;                     const float sg1 = fr >= 1 ? tg1 : pg1, sg2 = fr >= 2 ? tg2 : pg2, sv1 = fr >= 1 ? tv1 : pv1, sv2 = fr >= 2 ? tv2 : pv2;
;                     const float gg = gb + g0 * sg2 + g1 * sg1 + g2 * cgv;
;                     const float vv = vb + v0 * sv2 + v1 * sv1 + v2 * cvv;
;                     chain = gg * sigmoidf_(gg) * vv; acc[q >> 2][0][q & 3][n][i] = chain;
;                     pg1 = tg1; pg2 = tg2; pv1 = tv1; pv2 = tv2;
;                 }
	v_pk_mul_f32 v[184:185], v[228:229], v[184:185]
	v_mov_b32_e32 v182, v228
	v_add_f32_e32 v159, v185, v159
	v_add_f32_e32 v159, v184, v159
	v_mul_f32_e32 v184, v159, v155
	v_mov_b32_dpp v129, v187 row_ror:2 row_mask:0xf bank_mask:0xf
	v_mov_b32_dpp v153, v186 row_ror:2 row_mask:0xf bank_mask:0xf
	v_mov_b32_dpp v127, v187 row_ror:1 row_mask:0xf bank_mask:0xf
	v_mov_b32_dpp v131, v186 row_ror:1 row_mask:0xf bank_mask:0xf
	v_cndmask_b32_e64 v231, v121, v129, s[40:41]
	v_cndmask_b32_e64 v230, v125, v153, s[40:41]
	v_cndmask_b32_e64 v229, v127, v111, s[38:39]
	v_cndmask_b32_e64 v228, v131, v123, s[38:39]
	v_pk_fma_f32 v[230:231], v[138:139], v[230:231], v[188:189]
	v_pk_fma_f32 v[228:229], v[136:137], v[228:229], v[230:231]
	v_pk_fma_f32 v[186:187], v[182:183], v[186:187], v[228:229]
	v_mul_f32_e32 v111, 0xbfb8aa3b, v187
	v_exp_f32_e32 v111, v111
	s_nop 0
	v_add_f32_e32 v111, 1.0, v111
	v_rcp_f32_e32 v111, v111
	s_nop 0
	v_mul_f32_e32 v111, v187, v111
	v_mul_f32_e32 v185, v186, v111
	v_mov_b32_dpp v123, v115 row_ror:2 row_mask:0xf bank_mask:0xf
	v_mov_b32_dpp v155, v114 row_ror:2 row_mask:0xf bank_mask:0xf
	v_mov_b32_dpp v121, v115 row_ror:1 row_mask:0xf bank_mask:0xf
	v_mov_b32_dpp v125, v114 row_ror:1 row_mask:0xf bank_mask:0xf
	v_cndmask_b32_e64 v229, v129, v123, s[40:41]
	v_cndmask_b32_e64 v228, v153, v155, s[40:41]
	v_cndmask_b32_e64 v187, v121, v127, s[38:39]
	v_cndmask_b32_e64 v186, v125, v131, s[38:39]
	v_pk_fma_f32 v[228:229], v[138:139], v[228:229], v[188:189]
	v_pk_fma_f32 v[186:187], v[136:137], v[186:187], v[228:229]
	v_pk_fma_f32 v[114:115], v[182:183], v[114:115], v[186:187]
	v_mul_f32_e32 v111, 0xbfb8aa3b, v115
	v_exp_f32_e32 v111, v111
	s_nop 0
	v_add_f32_e32 v111, 1.0, v111
	v_rcp_f32_e32 v111, v111
	s_nop 0
	v_mul_f32_e32 v111, v115, v111
	v_mul_f32_e32 v186, v114, v111
	v_mov_b32_dpp v129, v99 row_ror:2 row_mask:0xf bank_mask:0xf
	v_mov_b32_dpp v153, v98 row_ror:2 row_mask:0xf bank_mask:0xf
	v_mov_b32_dpp v127, v99 row_ror:1 row_mask:0xf bank_mask:0xf
	v_mov_b32_dpp v131, v98 row_ror:1 row_mask:0xf bank_mask:0xf
	v_cndmask_b32_e64 v229, v123, v129, s[40:41]
	v_cndmask_b32_e64 v228, v155, v153, s[40:41]
	v_cndmask_b32_e64 v115, v127, v121, s[38:39]
	v_cndmask_b32_e64 v114, v131, v125, s[38:39]
	v_pk_fma_f32 v[228:229], v[138:139], v[228:229], v[188:189]
	v_pk_fma_f32 v[114:115], v[136:137], v[114:115], v[228:229]
	v_pk_fma_f32 v[98:99], v[182:183], v[98:99], v[114:115]
	v_mul_f32_e32 v111, 0xbfb8aa3b, v99
	v_exp_f32_e32 v111, v111
	s_nop 0
	v_add_f32_e32 v111, 1.0, v111
	v_rcp_f32_e32 v111, v111
	s_nop 0
	v_mul_f32_e32 v99, v99, v111
	v_mul_f32_e32 v187, v98, v99
	v_mov_b32_dpp v123, v191 row_ror:2 row_mask:0xf bank_mask:0xf
	v_mov_b32_dpp v155, v190 row_ror:2 row_mask:0xf bank_mask:0xf
	v_mov_b32_dpp v121, v191 row_ror:1 row_mask:0xf bank_mask:0xf
	v_mov_b32_dpp v125, v190 row_ror:1 row_mask:0xf bank_mask:0xf
	v_cndmask_b32_e64 v115, v129, v123, s[40:41]
	v_cndmask_b32_e64 v114, v153, v155, s[40:41]
	v_cndmask_b32_e64 v99, v121, v127, s[38:39]
	v_cndmask_b32_e64 v98, v125, v131, s[38:39]
	v_pk_fma_f32 v[114:115], v[138:139], v[114:115], v[188:189]
	v_pk_fma_f32 v[98:99], v[136:137], v[98:99], v[114:115]
	v_pk_fma_f32 v[98:99], v[182:183], v[190:191], v[98:99]
	v_mul_f32_e32 v111, 0xbfb8aa3b, v99
	v_exp_f32_e32 v111, v111
	s_nop 0
	v_add_f32_e32 v111, 1.0, v111
	v_rcp_f32_e32 v111, v111
	s_nop 0
	v_mul_f32_e32 v99, v99, v111
	v_mul_f32_e32 v190, v98, v99
	v_mov_b32_dpp v129, v193 row_ror:2 row_mask:0xf bank_mask:0xf
	v_mov_b32_dpp v153, v192 row_ror:2 row_mask:0xf bank_mask:0xf
	v_mov_b32_dpp v127, v193 row_ror:1 row_mask:0xf bank_mask:0xf
	v_mov_b32_dpp v131, v192 row_ror:1 row_mask:0xf bank_mask:0xf
	v_cndmask_b32_e64 v115, v123, v129, s[40:41]
	v_cndmask_b32_e64 v114, v155, v153, s[40:41]
	v_cndmask_b32_e64 v99, v127, v121, s[38:39]
	v_cndmask_b32_e64 v98, v131, v125, s[38:39]
	v_pk_fma_f32 v[114:115], v[138:139], v[114:115], v[188:189]
	v_pk_fma_f32 v[98:99], v[136:137], v[98:99], v[114:115]
	v_pk_fma_f32 v[98:99], v[182:183], v[192:193], v[98:99]
	v_mul_f32_e32 v111, 0xbfb8aa3b, v99
	v_exp_f32_e32 v111, v111
	s_nop 0
	v_add_f32_e32 v111, 1.0, v111
	v_rcp_f32_e32 v111, v111
	s_nop 0
	v_mul_f32_e32 v99, v99, v111
	v_mul_f32_e32 v191, v98, v99
	v_mov_b32_dpp v123, v133 row_ror:2 row_mask:0xf bank_mask:0xf
	v_mov_b32_dpp v155, v132 row_ror:2 row_mask:0xf bank_mask:0xf
	v_mov_b32_dpp v121, v133 row_ror:1 row_mask:0xf bank_mask:0xf
	v_mov_b32_dpp v125, v132 row_ror:1 row_mask:0xf bank_mask:0xf
	v_cndmask_b32_e64 v115, v129, v123, s[40:41]
	v_cndmask_b32_e64 v114, v153, v155, s[40:41]
	v_cndmask_b32_e64 v99, v121, v127, s[38:39]
	v_cndmask_b32_e64 v98, v125, v131, s[38:39]
	v_pk_fma_f32 v[114:115], v[138:139], v[114:115], v[188:189]
	v_pk_fma_f32 v[98:99], v[136:137], v[98:99], v[114:115]
	v_pk_fma_f32 v[98:99], v[182:183], v[132:133], v[98:99]
	v_mul_f32_e32 v111, 0xbfb8aa3b, v99
	v_exp_f32_e32 v111, v111
	s_nop 0
	v_add_f32_e32 v111, 1.0, v111
	v_rcp_f32_e32 v111, v111
	s_nop 0
	v_mul_f32_e32 v99, v99, v111
	v_mul_f32_e32 v192, v98, v99
	v_mov_b32_dpp v114, v135 row_ror:1 row_mask:0xf bank_mask:0xf
	v_mov_b32_dpp v115, v135 row_ror:2 row_mask:0xf bank_mask:0xf
	v_mov_b32_dpp v129, v134 row_ror:2 row_mask:0xf bank_mask:0xf
	v_mov_b32_dpp v127, v134 row_ror:1 row_mask:0xf bank_mask:0xf
	v_cndmask_b32_e64 v99, v114, v121, s[38:39]
	v_cndmask_b32_e64 v115, v123, v115, s[40:41]
	v_cndmask_b32_e64 v114, v155, v129, s[40:41]
	v_cndmask_b32_e64 v98, v127, v125, s[38:39]
	v_pk_fma_f32 v[114:115], v[138:139], v[114:115], v[188:189]
	s_nop 0
	v_pk_fma_f32 v[98:99], v[136:137], v[98:99], v[114:115]
	s_nop 0
	v_pk_fma_f32 v[98:99], v[182:183], v[134:135], v[98:99]
	s_nop 0
	v_mul_f32_e32 v111, 0xbfb8aa3b, v99
	v_exp_f32_e32 v111, v111
	s_nop 0
	v_add_f32_e32 v111, 1.0, v111
	v_rcp_f32_e32 v111, v111
	s_nop 0
	v_mul_f32_e32 v99, v99, v111
	v_mul_f32_e32 v136, v98, v99
	s_waitcnt vmcnt(0)
; __device__ __forceinline__ float sigmoidf_(float x) { return __builtin_amdgcn_rcpf(1.0f + __expf(-x)); }
; template <int N> __device__ __forceinline__ float dpp_ror(float v) { return __builtin_bit_cast(float, __builtin_amdgcn_update_dpp(0, __builtin_bit_cast(int, v), 0x120 + N, 0xf, 0xf, false)); }
;     __device__ __forceinline__ void operator()(Acc& acc, const Unit& u, int wr, int wc, int fr, int fq) const {
;     ...
;             for (int i = 0; i < 4; ++i) {
;                 const int cg_ = ch0 + 4 * n + i, cv_ = DFF + cg_;
;                 const float g0 = cw[cg_], g1 = cw[NUP + cg_], g2 = cw[2 * NUP + cg_], gb = cb[cg_];
;                 const float v0 = cw[cv_], v1 = cw[NUP + cv_], v2 = cw[2 * NUP + cv_], vb = cb[cv_];
;                 float pg1 = 0.f, pg2 = 0.f, pv1 = 0.f, pv2 = 0.f;
; #pragma unroll
;                 for (int q = 0; q < 8; ++q) {
;                     float cgv = acc[q >> 2][0][q & 3][n][i], cvv = acc[q >> 2][1][q & 3][n][i];
;                     asm volatile("" : "+v"(cgv), "+v"(cvv) : "v"(chain));
;                     const float tg1 = dpp_ror<1>(cgv), tg2 = dpp_ror<2>(cgv), tv1 = dpp_ror<1>(cvv), tv2 = dpp_ror<2>(cvv);
;                     const float sg1 = fr >= 1 ? tg1 : pg1, sg2 = fr >= 2 ? tg2 : pg2, sv1 = fr >= 1 ? tv1 : pv1, sv2 = fr >= 2 ? tv2 : pv2;
;                     const float gg = gb + g0 * sg2 + g1 * sg1 + g2 * cgv;
;                     const float vv = vb + v0 * sv2 + v1 * sv1 + v2 * cvv;
;                     chain = gg * sigmoidf_(gg) * vv; acc[q >> 2][0][q & 3][n][i] = chain;
;                     pg1 = tg1; pg2 = tg2; pv1 = tv1; pv2 = tv2;
;                 }
	v_mov_b32_e32 v115, v232
	v_mov_b32_e32 v99, v233
	v_mov_b32_e32 v98, v234
	v_mov_b32_e32 v133, v235
	v_mov_b32_e32 v132, v236
	v_mov_b32_e32 v114, v237
	v_mov_b32_e32 v139, v238
	v_mov_b32_e32 v138, v239
	global_load_dword v240, v[6:7], off offset:8
	global_load_dword v241, v[8:9], off offset:2056
	global_load_dword v242, v[10:11], off offset:8
	global_load_dword v243, v[16:17], off offset:8
	global_load_dword v244, v[20:21], off offset:3080
	global_load_dword v245, v[18:19], off offset:3080
	global_load_dword v246, v[22:23], off offset:1032
	global_load_dword v247, v[24:25], off offset:3080
	v_mov_b32_dpp v111, v176 row_ror:1 row_mask:0xf bank_mask:0xf
	v_mov_b32_dpp v121, v176 row_ror:2 row_mask:0xf bank_mask:0xf
	v_cndmask_b32_e64 v177, v111, 0, s[38:39]
	v_cndmask_b32_e64 v134, 0, v121, s[40:41]
	v_mov_b32_dpp v123, v178 row_ror:1 row_mask:0xf bank_mask:0xf
	v_cndmask_b32_e64 v179, v123, 0, s[38:39]
	v_mov_b32_dpp v125, v178 row_ror:2 row_mask:0xf bank_mask:0xf
	v_cndmask_b32_e64 v137, 0, v125, s[40:41]
	s_nop 0
	v_fma_f32 v155, v115, v134, v133
	v_pk_mul_f32 v[134:135], v[98:99], v[176:177]
	s_nop 0
	v_fma_f32 v137, v114, v137, v132
	v_add_f32_e32 v135, v135, v155
	v_add_f32_e32 v155, v134, v135
	v_mul_f32_e32 v134, 0xbfb8aa3b, v155
	v_exp_f32_e32 v159, v134
	v_mov_b32_e32 v135, v98
	s_nop 0
	v_pk_mul_f32 v[176:177], v[138:139], v[178:179]
	v_mov_b32_e32 v134, v138
	v_add_f32_e32 v98, 1.0, v159
	v_rcp_f32_e32 v138, v98
	v_add_f32_e32 v137, v177, v137
	v_add_f32_e32 v137, v176, v137
	v_mov_b32_e32 v98, v139
	v_mul_f32_e32 v138, v155, v138
	v_mul_f32_e32 v137, v137, v138
	v_mov_b32_dpp v129, v181 row_ror:2 row_mask:0xf bank_mask:0xf
	v_mov_b32_dpp v153, v180 row_ror:2 row_mask:0xf bank_mask:0xf
	v_mov_b32_dpp v127, v181 row_ror:1 row_mask:0xf bank_mask:0xf
	v_mov_b32_dpp v131, v180 row_ror:1 row_mask:0xf bank_mask:0xf
	v_cndmask_b32_e64 v177, v121, v129, s[40:41]
	v_cndmask_b32_e64 v176, v125, v153, s[40:41]
	v_cndmask_b32_e64 v139, v127, v111, s[38:39]
	v_cndmask_b32_e64 v138, v131, v123, s[38:39]
	v_pk_fma_f32 v[176:177], v[114:115], v[176:177], v[132:133]
	v_pk_fma_f32 v[138:139], v[98:99], v[138:139], v[176:177]
	v_pk_fma_f32 v[138:139], v[134:135], v[180:181], v[138:139]
	v_mul_f32_e32 v111, 0xbfb8aa3b, v139
	v_exp_f32_e32 v111, v111
	s_nop 0
	v_add_f32_e32 v111, 1.0, v111
	v_rcp_f32_e32 v111, v111
	s_nop 0
	v_mul_f32_e32 v111, v139, v111
	v_mul_f32_e32 v138, v138, v111
	v_mov_b32_dpp v123, v107 row_ror:2 row_mask:0xf bank_mask:0xf
	v_mov_b32_dpp v155, v106 row_ror:2 row_mask:0xf bank_mask:0xf
	v_mov_b32_dpp v121, v107 row_ror:1 row_mask:0xf bank_mask:0xf
	v_mov_b32_dpp v125, v106 row_ror:1 row_mask:0xf bank_mask:0xf
	v_cndmask_b32_e64 v179, v129, v123, s[40:41]
	v_cndmask_b32_e64 v178, v153, v155, s[40:41]
	v_cndmask_b32_e64 v177, v121, v127, s[38:39]
	v_cndmask_b32_e64 v176, v125, v131, s[38:39]
	v_pk_fma_f32 v[178:179], v[114:115], v[178:179], v[132:133]
	v_pk_fma_f32 v[176:177], v[98:99], v[176:177], v[178:179]
	v_pk_fma_f32 v[106:107], v[134:135], v[106:107], v[176:177]
	v_mul_f32_e32 v111, 0xbfb8aa3b, v107
	v_exp_f32_e32 v111, v111
	s_nop 0
	v_add_f32_e32 v111, 1.0, v111
	v_rcp_f32_e32 v111, v111
	s_nop 0
	v_mul_f32_e32 v107, v107, v111
	v_mul_f32_e32 v106, v106, v107
	v_mov_b32_dpp v129, v91 row_ror:2 row_mask:0xf bank_mask:0xf
	v_mov_b32_dpp v139, v90 row_ror:2 row_mask:0xf bank_mask:0xf
	v_mov_b32_dpp v127, v91 row_ror:1 row_mask:0xf bank_mask:0xf
	v_mov_b32_dpp v131, v90 row_ror:1 row_mask:0xf bank_mask:0xf
	v_cndmask_b32_e64 v179, v123, v129, s[40:41]
	v_cndmask_b32_e64 v178, v155, v139, s[40:41]
	v_cndmask_b32_e64 v177, v127, v121, s[38:39]
	v_cndmask_b32_e64 v176, v131, v125, s[38:39]
	v_pk_fma_f32 v[178:179], v[114:115], v[178:179], v[132:133]
	v_pk_fma_f32 v[176:177], v[98:99], v[176:177], v[178:179]
	v_pk_fma_f32 v[90:91], v[134:135], v[90:91], v[176:177]
	v_mul_f32_e32 v107, 0xbfb8aa3b, v91
	v_exp_f32_e32 v107, v107
	s_nop 0
	v_add_f32_e32 v107, 1.0, v107
	v_rcp_f32_e32 v107, v107
	s_nop 0
	v_mul_f32_e32 v91, v91, v107
	v_mul_f32_e32 v90, v90, v91
	v_mov_b32_dpp v121, v75 row_ror:2 row_mask:0xf bank_mask:0xf
	v_mov_b32_dpp v125, v74 row_ror:2 row_mask:0xf bank_mask:0xf
	v_mov_b32_dpp v111, v75 row_ror:1 row_mask:0xf bank_mask:0xf
	v_mov_b32_dpp v123, v74 row_ror:1 row_mask:0xf bank_mask:0xf
	v_cndmask_b32_e64 v179, v129, v121, s[40:41]
	v_cndmask_b32_e64 v178, v139, v125, s[40:41]
	v_cndmask_b32_e64 v177, v111, v127, s[38:39]
	v_cndmask_b32_e64 v176, v123, v131, s[38:39]
	v_pk_fma_f32 v[178:179], v[114:115], v[178:179], v[132:133]
	v_pk_fma_f32 v[176:177], v[98:99], v[176:177], v[178:179]
	v_pk_fma_f32 v[74:75], v[134:135], v[74:75], v[176:177]
	v_mul_f32_e32 v91, 0xbfb8aa3b, v75
	v_exp_f32_e32 v91, v91
	s_nop 0
	v_add_f32_e32 v91, 1.0, v91
	v_rcp_f32_e32 v91, v91
	s_nop 0
	v_mul_f32_e32 v75, v75, v91
	v_mul_f32_e32 v91, v74, v75
	v_mov_b32_dpp v129, v59 row_ror:2 row_mask:0xf bank_mask:0xf
	v_mov_b32_dpp v139, v58 row_ror:2 row_mask:0xf bank_mask:0xf
	v_mov_b32_dpp v127, v59 row_ror:1 row_mask:0xf bank_mask:0xf
	v_mov_b32_dpp v131, v58 row_ror:1 row_mask:0xf bank_mask:0xf
	v_cndmask_b32_e64 v177, v121, v129, s[40:41]
	v_cndmask_b32_e64 v176, v125, v139, s[40:41]
	v_cndmask_b32_e64 v75, v127, v111, s[38:39]
	v_cndmask_b32_e64 v74, v131, v123, s[38:39]
	v_pk_fma_f32 v[176:177], v[114:115], v[176:177], v[132:133]
	v_pk_fma_f32 v[74:75], v[98:99], v[74:75], v[176:177]
	v_pk_fma_f32 v[58:59], v[134:135], v[58:59], v[74:75]
	v_mul_f32_e32 v74, 0xbfb8aa3b, v59
	v_exp_f32_e32 v74, v74
	s_nop 0
	v_add_f32_e32 v74, 1.0, v74
	v_rcp_f32_e32 v74, v74
	s_nop 0
	v_mul_f32_e32 v59, v59, v74
	v_mul_f32_e32 v107, v58, v59
; __device__ __forceinline__ float sigmoidf_(float x) { return __builtin_amdgcn_rcpf(1.0f + __expf(-x)); }
; template <int N> __device__ __forceinline__ float dpp_ror(float v) { return __builtin_bit_cast(float, __builtin_amdgcn_update_dpp(0, __builtin_bit_cast(int, v), 0x120 + N, 0xf, 0xf, false)); }
;     __device__ __forceinline__ void operator()(Acc& acc, const Unit& u, int wr, int wc, int fr, int fq) const {
;     ...
;             for (int i = 0; i < 4; ++i) {
;                 const int cg_ = ch0 + 4 * n + i, cv_ = DFF + cg_;
;                 const float g0 = cw[cg_], g1 = cw[NUP + cg_], g2 = cw[2 * NUP + cg_], gb = cb[cg_];
;                 const float v0 = cw[cv_], v1 = cw[NUP + cv_], v2 = cw[2 * NUP + cv_], vb = cb[cv_];
;                 float pg1 = 0.f, pg2 = 0.f, pv1 = 0.f, pv2 = 0.f;
; #pragma unroll
;                 for (int q = 0; q < 8; ++q) {
;                     float cgv = acc[q >> 2][0][q & 3][n][i], cvv = acc[q >> 2][1][q & 3][n][i];
;                     asm volatile("" : "+v"(cgv), "+v"(cvv) : "v"(chain));
;                     const float tg1 = dpp_ror<1>(cgv), tg2 = dpp_ror<2>(cgv), tv1 = dpp_ror<1>(cvv), tv2 = dpp_ror<2>(cvv);
;                     const float sg1 = fr >= 1 ? tg1 : pg1, sg2 = fr >= 2 ? tg2 : pg2, sv1 = fr >= 1 ? tv1 : pv1, sv2 = fr >= 2 ? tv2 : pv2;
;                     const float gg = gb + g0 * sg2 + g1 * sg1 + g2 * cgv;
;                     const float vv = vb + v0 * sv2 + v1 * sv1 + v2 * cvv;
;                     chain = gg * sigmoidf_(gg) * vv; acc[q >> 2][0][q & 3][n][i] = chain;
;                     pg1 = tg1; pg2 = tg2; pv1 = tv1; pv2 = tv2;
;                 }
	v_mov_b32_dpp v121, v63 row_ror:2 row_mask:0xf bank_mask:0xf
	v_mov_b32_dpp v125, v62 row_ror:2 row_mask:0xf bank_mask:0xf
	v_mov_b32_dpp v111, v63 row_ror:1 row_mask:0xf bank_mask:0xf
	v_mov_b32_dpp v123, v62 row_ror:1 row_mask:0xf bank_mask:0xf
	v_cndmask_b32_e64 v75, v129, v121, s[40:41]
	v_cndmask_b32_e64 v74, v139, v125, s[40:41]
	v_cndmask_b32_e64 v59, v111, v127, s[38:39]
	v_cndmask_b32_e64 v58, v123, v131, s[38:39]
	v_pk_fma_f32 v[74:75], v[114:115], v[74:75], v[132:133]
	v_pk_fma_f32 v[58:59], v[98:99], v[58:59], v[74:75]
	v_pk_fma_f32 v[58:59], v[134:135], v[62:63], v[58:59]
	v_mul_f32_e32 v62, 0xbfb8aa3b, v59
	v_exp_f32_e32 v62, v62
	s_nop 0
	v_add_f32_e32 v62, 1.0, v62
	v_rcp_f32_e32 v62, v62
	s_nop 0
	v_mul_f32_e32 v59, v59, v62
	v_mul_f32_e32 v139, v58, v59
	v_mov_b32_dpp v63, v83 row_ror:1 row_mask:0xf bank_mask:0xf
	v_mov_b32_dpp v74, v83 row_ror:2 row_mask:0xf bank_mask:0xf
	v_mov_b32_dpp v127, v82 row_ror:2 row_mask:0xf bank_mask:0xf
	v_mov_b32_dpp v75, v82 row_ror:1 row_mask:0xf bank_mask:0xf
	v_cndmask_b32_e64 v59, v63, v111, s[38:39]
	v_cndmask_b32_e64 v63, v121, v74, s[40:41]
	v_cndmask_b32_e64 v62, v125, v127, s[40:41]
	v_cndmask_b32_e64 v58, v75, v123, s[38:39]
	v_pk_fma_f32 v[62:63], v[114:115], v[62:63], v[132:133]
	s_nop 0
	v_pk_fma_f32 v[58:59], v[98:99], v[58:59], v[62:63]
	s_nop 0
	v_pk_fma_f32 v[58:59], v[134:135], v[82:83], v[58:59]
	s_nop 0
	v_mul_f32_e32 v62, 0xbfb8aa3b, v59
	v_exp_f32_e32 v62, v62
	s_nop 0
	v_add_f32_e32 v62, 1.0, v62
	v_rcp_f32_e32 v62, v62
	s_nop 0
	v_mul_f32_e32 v59, v59, v62
	v_mul_f32_e32 v98, v58, v59
	s_waitcnt vmcnt(0)
	v_mov_b32_e32 v63, v240
	v_mov_b32_e32 v59, v241
	v_mov_b32_e32 v58, v242
	v_mov_b32_e32 v75, v243
	v_mov_b32_e32 v74, v244
	v_mov_b32_e32 v62, v245
	v_mov_b32_e32 v115, v246
	v_mov_b32_e32 v114, v247
	global_load_dword v232, v[6:7], off offset:12
	global_load_dword v233, v[8:9], off offset:2060
	global_load_dword v234, v[10:11], off offset:12
	global_load_dword v235, v[16:17], off offset:12
	global_load_dword v236, v[20:21], off offset:3084
	global_load_dword v237, v[18:19], off offset:3084
	global_load_dword v238, v[22:23], off offset:1036
	global_load_dword v239, v[24:25], off offset:3084
	v_mov_b32_dpp v111, v160 row_ror:1 row_mask:0xf bank_mask:0xf
	v_mov_b32_dpp v121, v160 row_ror:2 row_mask:0xf bank_mask:0xf
	v_cndmask_b32_e64 v161, v111, 0, s[38:39]
	v_cndmask_b32_e64 v82, 0, v121, s[40:41]
	v_mov_b32_dpp v123, v162 row_ror:1 row_mask:0xf bank_mask:0xf
	v_cndmask_b32_e64 v163, v123, 0, s[38:39]
	v_mov_b32_dpp v125, v162 row_ror:2 row_mask:0xf bank_mask:0xf
	v_cndmask_b32_e64 v99, 0, v125, s[40:41]
	s_nop 0
	v_fma_f32 v132, v63, v82, v75
	v_pk_mul_f32 v[82:83], v[58:59], v[160:161]
	s_nop 0
	v_fma_f32 v99, v62, v99, v74
	v_add_f32_e32 v83, v83, v132
	v_add_f32_e32 v135, v82, v83
	v_mul_f32_e32 v82, 0xbfb8aa3b, v135
	v_exp_f32_e32 v153, v82
	v_mov_b32_e32 v83, v58
	s_nop 0
	v_pk_mul_f32 v[132:133], v[114:115], v[162:163]
	v_mov_b32_e32 v82, v114
	v_add_f32_e32 v58, 1.0, v153
	v_rcp_f32_e32 v114, v58
	v_add_f32_e32 v99, v133, v99
	v_add_f32_e32 v99, v132, v99
	v_mov_b32_e32 v58, v115
	v_mul_f32_e32 v114, v135, v114
	v_mul_f32_e32 v99, v99, v114
	v_mov_b32_dpp v129, v175 row_ror:2 row_mask:0xf bank_mask:0xf
	v_mov_b32_dpp v134, v174 row_ror:2 row_mask:0xf bank_mask:0xf
	v_mov_b32_dpp v127, v175 row_ror:1 row_mask:0xf bank_mask:0xf
	v_mov_b32_dpp v131, v174 row_ror:1 row_mask:0xf bank_mask:0xf
	v_cndmask_b32_e64 v133, v121, v129, s[40:41]
	v_cndmask_b32_e64 v132, v125, v134, s[40:41]
	v_cndmask_b32_e64 v115, v127, v111, s[38:39]
	v_cndmask_b32_e64 v114, v131, v123, s[38:39]
	v_pk_fma_f32 v[132:133], v[62:63], v[132:133], v[74:75]
	v_pk_fma_f32 v[114:115], v[58:59], v[114:115], v[132:133]
	v_pk_fma_f32 v[114:115], v[82:83], v[174:175], v[114:115]
	v_mul_f32_e32 v111, 0xbfb8aa3b, v115
	v_exp_f32_e32 v111, v111
	s_nop 0
	v_add_f32_e32 v111, 1.0, v111
	v_rcp_f32_e32 v111, v111
	s_nop 0
	v_mul_f32_e32 v111, v115, v111
	v_mul_f32_e32 v114, v114, v111
	v_mov_b32_dpp v123, v105 row_ror:2 row_mask:0xf bank_mask:0xf
	v_mov_b32_dpp v153, v104 row_ror:2 row_mask:0xf bank_mask:0xf
	v_mov_b32_dpp v121, v105 row_ror:1 row_mask:0xf bank_mask:0xf
	v_mov_b32_dpp v125, v104 row_ror:1 row_mask:0xf bank_mask:0xf
	v_cndmask_b32_e64 v135, v129, v123, s[40:41]
	v_cndmask_b32_e64 v134, v134, v153, s[40:41]
	v_cndmask_b32_e64 v133, v121, v127, s[38:39]
	v_cndmask_b32_e64 v132, v125, v131, s[38:39]
	v_pk_fma_f32 v[134:135], v[62:63], v[134:135], v[74:75]
	v_pk_fma_f32 v[132:133], v[58:59], v[132:133], v[134:135]
	v_pk_fma_f32 v[104:105], v[82:83], v[104:105], v[132:133]
	v_mul_f32_e32 v111, 0xbfb8aa3b, v105
	v_exp_f32_e32 v111, v111
	s_nop 0
	v_add_f32_e32 v111, 1.0, v111
	v_rcp_f32_e32 v111, v111
	s_nop 0
	v_mul_f32_e32 v105, v105, v111
	v_mul_f32_e32 v104, v104, v105
	v_mov_b32_dpp v127, v89 row_ror:2 row_mask:0xf bank_mask:0xf
	v_mov_b32_dpp v131, v88 row_ror:2 row_mask:0xf bank_mask:0xf
	v_mov_b32_dpp v115, v89 row_ror:1 row_mask:0xf bank_mask:0xf
	v_mov_b32_dpp v129, v88 row_ror:1 row_mask:0xf bank_mask:0xf
	v_cndmask_b32_e64 v135, v123, v127, s[40:41]
	v_cndmask_b32_e64 v134, v153, v131, s[40:41]
	v_cndmask_b32_e64 v133, v115, v121, s[38:39]
	v_cndmask_b32_e64 v132, v129, v125, s[38:39]
	v_pk_fma_f32 v[134:135], v[62:63], v[134:135], v[74:75]
	v_pk_fma_f32 v[132:133], v[58:59], v[132:133], v[134:135]
	v_pk_fma_f32 v[88:89], v[82:83], v[88:89], v[132:133]
	v_mul_f32_e32 v105, 0xbfb8aa3b, v89
	v_exp_f32_e32 v105, v105
	s_nop 0
	v_add_f32_e32 v105, 1.0, v105
	v_rcp_f32_e32 v105, v105
	s_nop 0
	v_mul_f32_e32 v89, v89, v105
	v_mul_f32_e32 v88, v88, v89
; __device__ __forceinline__ float sigmoidf_(float x) { return __builtin_amdgcn_rcpf(1.0f + __expf(-x)); }
; template <int N> __device__ __forceinline__ float dpp_ror(float v) { return __builtin_bit_cast(float, __builtin_amdgcn_update_dpp(0, __builtin_bit_cast(int, v), 0x120 + N, 0xf, 0xf, false)); }
;     __device__ __forceinline__ void operator()(Acc& acc, const Unit& u, int wr, int wc, int fr, int fq) const {
;     ...
;             for (int i = 0; i < 4; ++i) {
;                 const int cg_ = ch0 + 4 * n + i, cv_ = DFF + cg_;
;                 const float g0 = cw[cg_], g1 = cw[NUP + cg_], g2 = cw[2 * NUP + cg_], gb = cb[cg_];
;                 const float v0 = cw[cv_], v1 = cw[NUP + cv_], v2 = cw[2 * NUP + cv_], vb = cb[cv_];
;                 float pg1 = 0.f, pg2 = 0.f, pv1 = 0.f, pv2 = 0.f;
; #pragma unroll
;                 for (int q = 0; q < 8; ++q) {
;                     float cgv = acc[q >> 2][0][q & 3][n][i], cvv = acc[q >> 2][1][q & 3][n][i];
;                     asm volatile("" : "+v"(cgv), "+v"(cvv) : "v"(chain));
;                     const float tg1 = dpp_ror<1>(cgv), tg2 = dpp_ror<2>(cgv), tv1 = dpp_ror<1>(cvv), tv2 = dpp_ror<2>(cvv);
;                     const float sg1 = fr >= 1 ? tg1 : pg1, sg2 = fr >= 2 ? tg2 : pg2, sv1 = fr >= 1 ? tv1 : pv1, sv2 = fr >= 2 ? tv2 : pv2;
;                     const float gg = gb + g0 * sg2 + g1 * sg1 + g2 * cgv;
;                     const float vv = vb + v0 * sv2 + v1 * sv1 + v2 * cvv;
;                     chain = gg * sigmoidf_(gg) * vv; acc[q >> 2][0][q & 3][n][i] = chain;
;                     pg1 = tg1; pg2 = tg2; pv1 = tv1; pv2 = tv2;
;                 }
	v_mov_b32_dpp v121, v73 row_ror:2 row_mask:0xf bank_mask:0xf
	v_mov_b32_dpp v125, v72 row_ror:2 row_mask:0xf bank_mask:0xf
	v_mov_b32_dpp v111, v73 row_ror:1 row_mask:0xf bank_mask:0xf
	v_mov_b32_dpp v123, v72 row_ror:1 row_mask:0xf bank_mask:0xf
	v_cndmask_b32_e64 v135, v127, v121, s[40:41]
	v_cndmask_b32_e64 v134, v131, v125, s[40:41]
	v_cndmask_b32_e64 v133, v111, v115, s[38:39]
	v_cndmask_b32_e64 v132, v123, v129, s[38:39]
	v_pk_fma_f32 v[134:135], v[62:63], v[134:135], v[74:75]
	v_pk_fma_f32 v[132:133], v[58:59], v[132:133], v[134:135]
	v_pk_fma_f32 v[72:73], v[82:83], v[72:73], v[132:133]
	v_mul_f32_e32 v89, 0xbfb8aa3b, v73
	v_exp_f32_e32 v89, v89
	s_nop 0
	v_add_f32_e32 v89, 1.0, v89
	v_rcp_f32_e32 v89, v89
	s_nop 0
	v_mul_f32_e32 v73, v73, v89
	v_mul_f32_e32 v72, v72, v73
	v_mov_b32_dpp v115, v57 row_ror:2 row_mask:0xf bank_mask:0xf
	v_mov_b32_dpp v129, v56 row_ror:2 row_mask:0xf bank_mask:0xf
	v_mov_b32_dpp v105, v57 row_ror:1 row_mask:0xf bank_mask:0xf
	v_mov_b32_dpp v127, v56 row_ror:1 row_mask:0xf bank_mask:0xf
	v_cndmask_b32_e64 v135, v121, v115, s[40:41]
	v_cndmask_b32_e64 v134, v125, v129, s[40:41]
	v_cndmask_b32_e64 v133, v105, v111, s[38:39]
	v_cndmask_b32_e64 v132, v127, v123, s[38:39]
	v_pk_fma_f32 v[134:135], v[62:63], v[134:135], v[74:75]
	v_pk_fma_f32 v[132:133], v[58:59], v[132:133], v[134:135]
	v_pk_fma_f32 v[56:57], v[82:83], v[56:57], v[132:133]
	v_mul_f32_e32 v73, 0xbfb8aa3b, v57
	v_exp_f32_e32 v73, v73
	s_nop 0
	v_add_f32_e32 v73, 1.0, v73
	v_rcp_f32_e32 v73, v73
	s_nop 0
	v_mul_f32_e32 v57, v57, v73
	v_mul_f32_e32 v73, v56, v57
	v_mov_b32_dpp v121, v43 row_ror:2 row_mask:0xf bank_mask:0xf
	v_mov_b32_dpp v125, v42 row_ror:2 row_mask:0xf bank_mask:0xf
	v_mov_b32_dpp v111, v43 row_ror:1 row_mask:0xf bank_mask:0xf
	v_mov_b32_dpp v123, v42 row_ror:1 row_mask:0xf bank_mask:0xf
	v_cndmask_b32_e64 v133, v115, v121, s[40:41]
	v_cndmask_b32_e64 v132, v129, v125, s[40:41]
	v_cndmask_b32_e64 v57, v111, v105, s[38:39]
	v_cndmask_b32_e64 v56, v123, v127, s[38:39]
	v_pk_fma_f32 v[132:133], v[62:63], v[132:133], v[74:75]
	v_pk_fma_f32 v[56:57], v[58:59], v[56:57], v[132:133]
	v_pk_fma_f32 v[42:43], v[82:83], v[42:43], v[56:57]
	v_mul_f32_e32 v56, 0xbfb8aa3b, v43
	v_exp_f32_e32 v56, v56
	s_nop 0
	v_add_f32_e32 v56, 1.0, v56
	v_rcp_f32_e32 v56, v56
	s_nop 0
	v_mul_f32_e32 v43, v43, v56
	v_mul_f32_e32 v89, v42, v43
	v_mov_b32_dpp v57, v51 row_ror:1 row_mask:0xf bank_mask:0xf
	v_mov_b32_dpp v105, v51 row_ror:2 row_mask:0xf bank_mask:0xf
	v_mov_b32_dpp v127, v50 row_ror:2 row_mask:0xf bank_mask:0xf
	v_mov_b32_dpp v115, v50 row_ror:1 row_mask:0xf bank_mask:0xf
	v_cndmask_b32_e64 v43, v57, v111, s[38:39]
	v_cndmask_b32_e64 v57, v121, v105, s[40:41]
	v_cndmask_b32_e64 v56, v125, v127, s[40:41]
	v_cndmask_b32_e64 v42, v115, v123, s[38:39]
	v_pk_fma_f32 v[56:57], v[62:63], v[56:57], v[74:75]
	s_nop 0
	v_pk_fma_f32 v[42:43], v[58:59], v[42:43], v[56:57]
	s_nop 0
	v_pk_fma_f32 v[42:43], v[82:83], v[50:51], v[42:43]
	s_nop 0
	v_mul_f32_e32 v50, 0xbfb8aa3b, v43
	v_exp_f32_e32 v50, v50
	s_nop 0
	v_add_f32_e32 v50, 1.0, v50
	v_rcp_f32_e32 v50, v50
	s_nop 0
	v_mul_f32_e32 v43, v43, v50
	v_mul_f32_e32 v62, v42, v43
	s_waitcnt vmcnt(0)
	v_mov_b32_e32 v51, v232
	v_mov_b32_e32 v43, v233
	v_mov_b32_e32 v42, v234
	v_mov_b32_e32 v57, v235
	v_mov_b32_e32 v56, v236
	v_mov_b32_e32 v50, v237
	v_mov_b32_e32 v75, v238
	v_mov_b32_e32 v74, v239
	global_load_dword v240, v[6:7], off offset:16
	global_load_dword v241, v[8:9], off offset:2064
	global_load_dword v242, v[10:11], off offset:16
	global_load_dword v243, v[16:17], off offset:16
	global_load_dword v244, v[20:21], off offset:3088
	global_load_dword v245, v[18:19], off offset:3088
	global_load_dword v246, v[22:23], off offset:1040
	global_load_dword v247, v[24:25], off offset:3088
	v_mov_b32_dpp v105, v154 row_ror:1 row_mask:0xf bank_mask:0xf
	v_mov_b32_dpp v111, v154 row_ror:2 row_mask:0xf bank_mask:0xf
	v_cndmask_b32_e64 v155, v105, 0, s[38:39]
	v_cndmask_b32_e64 v58, 0, v111, s[40:41]
	v_mov_b32_dpp v115, v158 row_ror:1 row_mask:0xf bank_mask:0xf
	v_cndmask_b32_e64 v159, v115, 0, s[38:39]
	v_mov_b32_dpp v121, v158 row_ror:2 row_mask:0xf bank_mask:0xf
	v_cndmask_b32_e64 v63, 0, v121, s[40:41]
	s_nop 0
	v_fma_f32 v82, v51, v58, v57
	v_pk_mul_f32 v[58:59], v[42:43], v[154:155]
	s_nop 0
	v_fma_f32 v63, v50, v63, v56
	v_add_f32_e32 v59, v59, v82
	v_add_f32_e32 v131, v58, v59
	v_mul_f32_e32 v58, 0xbfb8aa3b, v131
	v_exp_f32_e32 v132, v58
	v_mov_b32_e32 v59, v42
	s_nop 0
	v_pk_mul_f32 v[82:83], v[74:75], v[158:159]
	v_mov_b32_e32 v58, v74
	v_add_f32_e32 v42, 1.0, v132
	v_rcp_f32_e32 v74, v42
	v_add_f32_e32 v63, v83, v63
	v_add_f32_e32 v63, v82, v63
	v_mov_b32_e32 v42, v75
	v_mul_f32_e32 v74, v131, v74
	v_mul_f32_e32 v63, v63, v74
	v_mov_b32_dpp v125, v157 row_ror:2 row_mask:0xf bank_mask:0xf
	v_mov_b32_dpp v129, v156 row_ror:2 row_mask:0xf bank_mask:0xf
	v_mov_b32_dpp v123, v157 row_ror:1 row_mask:0xf bank_mask:0xf
	v_mov_b32_dpp v127, v156 row_ror:1 row_mask:0xf bank_mask:0xf
	v_cndmask_b32_e64 v83, v111, v125, s[40:41]
	v_cndmask_b32_e64 v82, v121, v129, s[40:41]
	v_cndmask_b32_e64 v75, v123, v105, s[38:39]
	v_cndmask_b32_e64 v74, v127, v115, s[38:39]
	v_pk_fma_f32 v[82:83], v[50:51], v[82:83], v[56:57]
	v_pk_fma_f32 v[74:75], v[42:43], v[74:75], v[82:83]
	v_pk_fma_f32 v[74:75], v[58:59], v[156:157], v[74:75]
	v_mul_f32_e32 v82, 0xbfb8aa3b, v75
	v_exp_f32_e32 v82, v82
	s_nop 0
	v_add_f32_e32 v82, 1.0, v82
	v_rcp_f32_e32 v82, v82
	s_nop 0
	v_mul_f32_e32 v75, v75, v82
	v_mul_f32_e32 v74, v74, v75
	v_mov_b32_dpp v111, v103 row_ror:2 row_mask:0xf bank_mask:0xf
	v_mov_b32_dpp v121, v102 row_ror:2 row_mask:0xf bank_mask:0xf
; __device__ __forceinline__ float sigmoidf_(float x) { return __builtin_amdgcn_rcpf(1.0f + __expf(-x)); }
; template <int N> __device__ __forceinline__ float dpp_ror(float v) { return __builtin_bit_cast(float, __builtin_amdgcn_update_dpp(0, __builtin_bit_cast(int, v), 0x120 + N, 0xf, 0xf, false)); }
;     __device__ __forceinline__ void operator()(Acc& acc, const Unit& u, int wr, int wc, int fr, int fq) const {
;     ...
;             for (int i = 0; i < 4; ++i) {
;                 const int cg_ = ch0 + 4 * n + i, cv_ = DFF + cg_;
;                 const float g0 = cw[cg_], g1 = cw[NUP + cg_], g2 = cw[2 * NUP + cg_], gb = cb[cg_];
;                 const float v0 = cw[cv_], v1 = cw[NUP + cv_], v2 = cw[2 * NUP + cv_], vb = cb[cv_];
;                 float pg1 = 0.f, pg2 = 0.f, pv1 = 0.f, pv2 = 0.f;
; #pragma unroll
;                 for (int q = 0; q < 8; ++q) {
;                     float cgv = acc[q >> 2][0][q & 3][n][i], cvv = acc[q >> 2][1][q & 3][n][i];
;                     asm volatile("" : "+v"(cgv), "+v"(cvv) : "v"(chain));
;                     const float tg1 = dpp_ror<1>(cgv), tg2 = dpp_ror<2>(cgv), tv1 = dpp_ror<1>(cvv), tv2 = dpp_ror<2>(cvv);
;                     const float sg1 = fr >= 1 ? tg1 : pg1, sg2 = fr >= 2 ? tg2 : pg2, sv1 = fr >= 1 ? tv1 : pv1, sv2 = fr >= 2 ? tv2 : pv2;
;                     const float gg = gb + g0 * sg2 + g1 * sg1 + g2 * cgv;
;                     const float vv = vb + v0 * sv2 + v1 * sv1 + v2 * cvv;
;                     chain = gg * sigmoidf_(gg) * vv; acc[q >> 2][0][q & 3][n][i] = chain;
;                     pg1 = tg1; pg2 = tg2; pv1 = tv1; pv2 = tv2;
;                 }
	v_mov_b32_dpp v105, v103 row_ror:1 row_mask:0xf bank_mask:0xf
	v_mov_b32_dpp v115, v102 row_ror:1 row_mask:0xf bank_mask:0xf
	v_cndmask_b32_e64 v133, v125, v111, s[40:41]
	v_cndmask_b32_e64 v132, v129, v121, s[40:41]
	v_cndmask_b32_e64 v83, v105, v123, s[38:39]
	v_cndmask_b32_e64 v82, v115, v127, s[38:39]
	v_pk_fma_f32 v[132:133], v[50:51], v[132:133], v[56:57]
	v_pk_fma_f32 v[82:83], v[42:43], v[82:83], v[132:133]
	v_pk_fma_f32 v[82:83], v[58:59], v[102:103], v[82:83]
	v_mul_f32_e32 v75, 0xbfb8aa3b, v83
	v_exp_f32_e32 v75, v75
	s_nop 0
	v_add_f32_e32 v75, 1.0, v75
	v_rcp_f32_e32 v75, v75
	s_nop 0
	v_mul_f32_e32 v75, v83, v75
	v_mul_f32_e32 v75, v82, v75
	v_mov_b32_dpp v125, v87 row_ror:2 row_mask:0xf bank_mask:0xf
	v_mov_b32_dpp v129, v86 row_ror:2 row_mask:0xf bank_mask:0xf
	v_mov_b32_dpp v123, v87 row_ror:1 row_mask:0xf bank_mask:0xf
	v_mov_b32_dpp v127, v86 row_ror:1 row_mask:0xf bank_mask:0xf
	v_cndmask_b32_e64 v103, v111, v125, s[40:41]
	v_cndmask_b32_e64 v102, v121, v129, s[40:41]
	v_cndmask_b32_e64 v83, v123, v105, s[38:39]
	v_cndmask_b32_e64 v82, v127, v115, s[38:39]
	v_pk_fma_f32 v[102:103], v[50:51], v[102:103], v[56:57]
	v_pk_fma_f32 v[82:83], v[42:43], v[82:83], v[102:103]
	v_pk_fma_f32 v[82:83], v[58:59], v[86:87], v[82:83]
	v_mul_f32_e32 v86, 0xbfb8aa3b, v83
	v_exp_f32_e32 v86, v86
	s_nop 0
	v_add_f32_e32 v86, 1.0, v86
	v_rcp_f32_e32 v86, v86
	s_nop 0
	v_mul_f32_e32 v83, v83, v86
	v_mul_f32_e32 v82, v82, v83
	v_mov_b32_dpp v111, v71 row_ror:2 row_mask:0xf bank_mask:0xf
	v_mov_b32_dpp v121, v70 row_ror:2 row_mask:0xf bank_mask:0xf
	v_mov_b32_dpp v105, v71 row_ror:1 row_mask:0xf bank_mask:0xf
	v_mov_b32_dpp v115, v70 row_ror:1 row_mask:0xf bank_mask:0xf
	v_cndmask_b32_e64 v103, v125, v111, s[40:41]
	v_cndmask_b32_e64 v102, v129, v121, s[40:41]
	v_cndmask_b32_e64 v87, v105, v123, s[38:39]
	v_cndmask_b32_e64 v86, v115, v127, s[38:39]
	v_pk_fma_f32 v[102:103], v[50:51], v[102:103], v[56:57]
	v_pk_fma_f32 v[86:87], v[42:43], v[86:87], v[102:103]
	v_pk_fma_f32 v[70:71], v[58:59], v[70:71], v[86:87]
	v_mul_f32_e32 v83, 0xbfb8aa3b, v71
	v_exp_f32_e32 v83, v83
	s_nop 0
	v_add_f32_e32 v83, 1.0, v83
	v_rcp_f32_e32 v83, v83
	s_nop 0
	v_mul_f32_e32 v71, v71, v83
	v_mul_f32_e32 v70, v70, v71
	v_mov_b32_dpp v125, v55 row_ror:2 row_mask:0xf bank_mask:0xf
	v_mov_b32_dpp v129, v54 row_ror:2 row_mask:0xf bank_mask:0xf
	v_mov_b32_dpp v123, v55 row_ror:1 row_mask:0xf bank_mask:0xf
	v_mov_b32_dpp v127, v54 row_ror:1 row_mask:0xf bank_mask:0xf
	v_cndmask_b32_e64 v103, v111, v125, s[40:41]
	v_cndmask_b32_e64 v102, v121, v129, s[40:41]
	v_cndmask_b32_e64 v87, v123, v105, s[38:39]
	v_cndmask_b32_e64 v86, v127, v115, s[38:39]
	v_pk_fma_f32 v[102:103], v[50:51], v[102:103], v[56:57]
	v_pk_fma_f32 v[86:87], v[42:43], v[86:87], v[102:103]
	v_pk_fma_f32 v[54:55], v[58:59], v[54:55], v[86:87]
	v_mul_f32_e32 v71, 0xbfb8aa3b, v55
	v_exp_f32_e32 v71, v71
	s_nop 0
	v_add_f32_e32 v71, 1.0, v71
	v_rcp_f32_e32 v71, v71
	s_nop 0
	v_mul_f32_e32 v55, v55, v71
	v_mul_f32_e32 v55, v54, v55
	v_mov_b32_dpp v105, v39 row_ror:2 row_mask:0xf bank_mask:0xf
	v_mov_b32_dpp v115, v38 row_ror:2 row_mask:0xf bank_mask:0xf
	v_mov_b32_dpp v83, v39 row_ror:1 row_mask:0xf bank_mask:0xf
	v_mov_b32_dpp v111, v38 row_ror:1 row_mask:0xf bank_mask:0xf
	v_cndmask_b32_e64 v103, v125, v105, s[40:41]
	v_cndmask_b32_e64 v102, v129, v115, s[40:41]
	v_cndmask_b32_e64 v87, v83, v123, s[38:39]
	v_cndmask_b32_e64 v86, v111, v127, s[38:39]
	v_pk_fma_f32 v[102:103], v[50:51], v[102:103], v[56:57]
	s_nop 0
	v_pk_fma_f32 v[86:87], v[42:43], v[86:87], v[102:103]
	v_pk_fma_f32 v[38:39], v[58:59], v[38:39], v[86:87]
	v_mul_f32_e32 v54, 0xbfb8aa3b, v39
	v_exp_f32_e32 v54, v54
	s_nop 0
	v_add_f32_e32 v54, 1.0, v54
	v_rcp_f32_e32 v54, v54
	s_nop 0
	v_mul_f32_e32 v39, v39, v54
	v_mul_f32_e32 v71, v38, v39
	v_mov_b32_dpp v86, v41 row_ror:1 row_mask:0xf bank_mask:0xf
	v_mov_b32_dpp v87, v41 row_ror:2 row_mask:0xf bank_mask:0xf
	v_mov_b32_dpp v103, v40 row_ror:2 row_mask:0xf bank_mask:0xf
	v_mov_b32_dpp v102, v40 row_ror:1 row_mask:0xf bank_mask:0xf
	v_cndmask_b32_e64 v39, v86, v83, s[38:39]
	v_cndmask_b32_e64 v87, v105, v87, s[40:41]
	v_cndmask_b32_e64 v86, v115, v103, s[40:41]
	v_cndmask_b32_e64 v38, v102, v111, s[38:39]
	v_pk_fma_f32 v[50:51], v[50:51], v[86:87], v[56:57]
	s_nop 0
	v_pk_fma_f32 v[38:39], v[42:43], v[38:39], v[50:51]
	s_nop 0
	v_pk_fma_f32 v[38:39], v[58:59], v[40:41], v[38:39]
	s_nop 0
	v_mul_f32_e32 v40, 0xbfb8aa3b, v39
	v_exp_f32_e32 v40, v40
	s_nop 0
	v_add_f32_e32 v40, 1.0, v40
	v_rcp_f32_e32 v40, v40
	s_nop 0
	v_mul_f32_e32 v39, v39, v40
	v_mul_f32_e32 v54, v38, v39
	s_waitcnt vmcnt(0)
; __device__ __forceinline__ float sigmoidf_(float x) { return __builtin_amdgcn_rcpf(1.0f + __expf(-x)); }
; template <int N> __device__ __forceinline__ float dpp_ror(float v) { return __builtin_bit_cast(float, __builtin_amdgcn_update_dpp(0, __builtin_bit_cast(int, v), 0x120 + N, 0xf, 0xf, false)); }
;     __device__ __forceinline__ void operator()(Acc& acc, const Unit& u, int wr, int wc, int fr, int fq) const {
;     ...
;             for (int i = 0; i < 4; ++i) {
;                 const int cg_ = ch0 + 4 * n + i, cv_ = DFF + cg_;
;                 const float g0 = cw[cg_], g1 = cw[NUP + cg_], g2 = cw[2 * NUP + cg_], gb = cb[cg_];
;                 const float v0 = cw[cv_], v1 = cw[NUP + cv_], v2 = cw[2 * NUP + cv_], vb = cb[cv_];
;                 float pg1 = 0.f, pg2 = 0.f, pv1 = 0.f, pv2 = 0.f;
; #pragma unroll
;                 for (int q = 0; q < 8; ++q) {
;                     float cgv = acc[q >> 2][0][q & 3][n][i], cvv = acc[q >> 2][1][q & 3][n][i];
;                     asm volatile("" : "+v"(cgv), "+v"(cvv) : "v"(chain));
;                     const float tg1 = dpp_ror<1>(cgv), tg2 = dpp_ror<2>(cgv), tv1 = dpp_ror<1>(cvv), tv2 = dpp_ror<2>(cvv);
;                     const float sg1 = fr >= 1 ? tg1 : pg1, sg2 = fr >= 2 ? tg2 : pg2, sv1 = fr >= 1 ? tv1 : pv1, sv2 = fr >= 2 ? tv2 : pv2;
;                     const float gg = gb + g0 * sg2 + g1 * sg1 + g2 * cgv;
;                     const float vv = vb + v0 * sv2 + v1 * sv1 + v2 * cvv;
;                     chain = gg * sigmoidf_(gg) * vv; acc[q >> 2][0][q & 3][n][i] = chain;
;                     pg1 = tg1; pg2 = tg2; pv1 = tv1; pv2 = tv2;
;                 }
	v_mov_b32_e32 v41, v240
	v_mov_b32_e32 v39, v241
	v_mov_b32_e32 v38, v242
	v_mov_b32_e32 v43, v243
	v_mov_b32_e32 v42, v244
	v_mov_b32_e32 v40, v245
	v_mov_b32_e32 v57, v246
	v_mov_b32_e32 v56, v247
	global_load_dword v232, v[6:7], off offset:20
	global_load_dword v233, v[8:9], off offset:2068
	global_load_dword v234, v[10:11], off offset:20
	global_load_dword v235, v[16:17], off offset:20
	global_load_dword v236, v[20:21], off offset:3092
	global_load_dword v237, v[18:19], off offset:3092
	global_load_dword v238, v[22:23], off offset:1044
	global_load_dword v239, v[24:25], off offset:3092
	v_mov_b32_dpp v83, v130 row_ror:1 row_mask:0xf bank_mask:0xf
	v_mov_b32_dpp v86, v130 row_ror:2 row_mask:0xf bank_mask:0xf
	v_cndmask_b32_e64 v131, v83, 0, s[38:39]
	v_cndmask_b32_e64 v50, 0, v86, s[40:41]
	v_mov_b32_dpp v87, v152 row_ror:1 row_mask:0xf bank_mask:0xf
	v_mov_b32_dpp v102, v152 row_ror:2 row_mask:0xf bank_mask:0xf
	v_cndmask_b32_e64 v153, v87, 0, s[38:39]
	v_cndmask_b32_e64 v58, 0, v102, s[40:41]
	s_nop 0
	v_fma_f32 v59, v41, v50, v43
	v_pk_mul_f32 v[50:51], v[38:39], v[130:131]
	s_nop 0
	v_fma_f32 v121, v40, v58, v42
	v_add_f32_e32 v51, v51, v59
	v_add_f32_e32 v123, v50, v51
	v_mul_f32_e32 v50, 0xbfb8aa3b, v123
	v_exp_f32_e32 v125, v50
	v_mov_b32_e32 v51, v38
	s_nop 0
	v_pk_mul_f32 v[58:59], v[56:57], v[152:153]
	v_mov_b32_e32 v50, v56
	v_add_f32_e32 v38, 1.0, v125
	v_rcp_f32_e32 v56, v38
	v_mov_b32_e32 v38, v57
	v_add_f32_e32 v57, v59, v121
	v_add_f32_e32 v57, v58, v57
	v_mul_f32_e32 v56, v123, v56
	v_mul_f32_e32 v56, v57, v56
	v_mov_b32_dpp v105, v119 row_ror:2 row_mask:0xf bank_mask:0xf
	v_mov_b32_dpp v111, v118 row_ror:1 row_mask:0xf bank_mask:0xf
	v_mov_b32_dpp v115, v118 row_ror:2 row_mask:0xf bank_mask:0xf
	v_mov_b32_dpp v103, v119 row_ror:1 row_mask:0xf bank_mask:0xf
	v_cndmask_b32_e64 v58, v111, v87, s[38:39]
	v_cndmask_b32_e64 v87, v86, v105, s[40:41]
	v_cndmask_b32_e64 v86, v102, v115, s[40:41]
	v_cndmask_b32_e64 v59, v103, v83, s[38:39]
	v_pk_fma_f32 v[86:87], v[40:41], v[86:87], v[42:43]
	v_pk_fma_f32 v[58:59], v[38:39], v[58:59], v[86:87]
	v_pk_fma_f32 v[58:59], v[50:51], v[118:119], v[58:59]
	v_mul_f32_e32 v57, 0xbfb8aa3b, v59
	v_exp_f32_e32 v57, v57
	s_nop 0
	v_add_f32_e32 v57, 1.0, v57
	v_rcp_f32_e32 v57, v57
	s_nop 0
	v_mul_f32_e32 v57, v59, v57
	v_mul_f32_e32 v57, v58, v57
	v_mov_b32_dpp v102, v101 row_ror:2 row_mask:0xf bank_mask:0xf
	v_mov_b32_dpp v119, v100 row_ror:2 row_mask:0xf bank_mask:0xf
	v_mov_b32_dpp v83, v101 row_ror:1 row_mask:0xf bank_mask:0xf
	v_mov_b32_dpp v118, v100 row_ror:1 row_mask:0xf bank_mask:0xf
	v_cndmask_b32_e64 v87, v105, v102, s[40:41]
	v_cndmask_b32_e64 v86, v115, v119, s[40:41]
	v_cndmask_b32_e64 v59, v83, v103, s[38:39]
	v_cndmask_b32_e64 v58, v118, v111, s[38:39]
	v_pk_fma_f32 v[86:87], v[40:41], v[86:87], v[42:43]
	v_pk_fma_f32 v[58:59], v[38:39], v[58:59], v[86:87]
	v_pk_fma_f32 v[58:59], v[50:51], v[100:101], v[58:59]
	v_mul_f32_e32 v86, 0xbfb8aa3b, v59
	v_exp_f32_e32 v86, v86
	s_nop 0
	v_add_f32_e32 v86, 1.0, v86
	v_rcp_f32_e32 v86, v86
	s_nop 0
	v_mul_f32_e32 v59, v59, v86
	v_mul_f32_e32 v58, v58, v59
	v_mov_b32_dpp v105, v85 row_ror:2 row_mask:0xf bank_mask:0xf
	v_mov_b32_dpp v115, v84 row_ror:2 row_mask:0xf bank_mask:0xf
	v_mov_b32_dpp v103, v85 row_ror:1 row_mask:0xf bank_mask:0xf
	v_mov_b32_dpp v111, v84 row_ror:1 row_mask:0xf bank_mask:0xf
	v_cndmask_b32_e64 v101, v102, v105, s[40:41]
	v_cndmask_b32_e64 v100, v119, v115, s[40:41]
	v_cndmask_b32_e64 v87, v103, v83, s[38:39]
	v_cndmask_b32_e64 v86, v111, v118, s[38:39]
	v_pk_fma_f32 v[100:101], v[40:41], v[100:101], v[42:43]
	v_pk_fma_f32 v[86:87], v[38:39], v[86:87], v[100:101]
	v_pk_fma_f32 v[84:85], v[50:51], v[84:85], v[86:87]
	v_mul_f32_e32 v59, 0xbfb8aa3b, v85
	v_exp_f32_e32 v59, v59
	s_nop 0
	v_add_f32_e32 v59, 1.0, v59
	v_rcp_f32_e32 v59, v59
	s_nop 0
	v_mul_f32_e32 v59, v85, v59
	v_mul_f32_e32 v59, v84, v59
	v_mov_b32_dpp v100, v69 row_ror:2 row_mask:0xf bank_mask:0xf
	v_mov_b32_dpp v102, v68 row_ror:2 row_mask:0xf bank_mask:0xf
	v_mov_b32_dpp v83, v69 row_ror:1 row_mask:0xf bank_mask:0xf
	v_mov_b32_dpp v101, v68 row_ror:1 row_mask:0xf bank_mask:0xf
	v_cndmask_b32_e64 v87, v105, v100, s[40:41]
	v_cndmask_b32_e64 v86, v115, v102, s[40:41]
	v_cndmask_b32_e64 v85, v83, v103, s[38:39]
	v_cndmask_b32_e64 v84, v101, v111, s[38:39]
	v_pk_fma_f32 v[86:87], v[40:41], v[86:87], v[42:43]
	v_pk_fma_f32 v[84:85], v[38:39], v[84:85], v[86:87]
	v_pk_fma_f32 v[68:69], v[50:51], v[68:69], v[84:85]
	v_mul_f32_e32 v84, 0xbfb8aa3b, v69
	v_exp_f32_e32 v84, v84
	s_nop 0
	v_add_f32_e32 v84, 1.0, v84
	v_rcp_f32_e32 v84, v84
	s_nop 0
	v_mul_f32_e32 v69, v69, v84
	v_mul_f32_e32 v68, v68, v69
	v_mov_b32_dpp v105, v53 row_ror:2 row_mask:0xf bank_mask:0xf
	v_mov_b32_dpp v115, v52 row_ror:2 row_mask:0xf bank_mask:0xf
	v_mov_b32_dpp v103, v53 row_ror:1 row_mask:0xf bank_mask:0xf
	v_mov_b32_dpp v111, v52 row_ror:1 row_mask:0xf bank_mask:0xf
	v_cndmask_b32_e64 v87, v100, v105, s[40:41]
	v_cndmask_b32_e64 v86, v102, v115, s[40:41]
	v_cndmask_b32_e64 v85, v103, v83, s[38:39]
	v_cndmask_b32_e64 v84, v111, v101, s[38:39]
	v_pk_fma_f32 v[86:87], v[40:41], v[86:87], v[42:43]
	v_pk_fma_f32 v[84:85], v[38:39], v[84:85], v[86:87]
	v_pk_fma_f32 v[52:53], v[50:51], v[52:53], v[84:85]
	v_mul_f32_e32 v69, 0xbfb8aa3b, v53
	v_exp_f32_e32 v69, v69
	s_nop 0
	v_add_f32_e32 v69, 1.0, v69
	v_rcp_f32_e32 v69, v69
	s_nop 0
	v_mul_f32_e32 v53, v53, v69
	v_mul_f32_e32 v52, v52, v53
	v_mov_b32_dpp v100, v37 row_ror:2 row_mask:0xf bank_mask:0xf
	v_mov_b32_dpp v102, v36 row_ror:2 row_mask:0xf bank_mask:0xf
	v_mov_b32_dpp v83, v37 row_ror:1 row_mask:0xf bank_mask:0xf
	v_mov_b32_dpp v101, v36 row_ror:1 row_mask:0xf bank_mask:0xf
	v_cndmask_b32_e64 v87, v105, v100, s[40:41]
	v_cndmask_b32_e64 v86, v115, v102, s[40:41]
	v_cndmask_b32_e64 v85, v83, v103, s[38:39]
	v_cndmask_b32_e64 v84, v101, v111, s[38:39]
	v_pk_fma_f32 v[86:87], v[40:41], v[86:87], v[42:43]
	s_nop 0
	v_pk_fma_f32 v[84:85], v[38:39], v[84:85], v[86:87]
	v_pk_fma_f32 v[36:37], v[50:51], v[36:37], v[84:85]
	v_mul_f32_e32 v53, 0xbfb8aa3b, v37
	v_exp_f32_e32 v53, v53
	s_nop 0
	v_add_f32_e32 v53, 1.0, v53
	v_rcp_f32_e32 v53, v53
	s_nop 0
	v_mul_f32_e32 v37, v37, v53
	v_mul_f32_e32 v53, v36, v37
	v_mov_b32_dpp v84, v35 row_ror:2 row_mask:0xf bank_mask:0xf
	v_mov_b32_dpp v85, v34 row_ror:1 row_mask:0xf bank_mask:0xf
	v_mov_b32_dpp v86, v34 row_ror:2 row_mask:0xf bank_mask:0xf
	v_mov_b32_dpp v69, v35 row_ror:1 row_mask:0xf bank_mask:0xf
	v_cndmask_b32_e64 v36, v85, v101, s[38:39]
	v_cndmask_b32_e64 v85, v100, v84, s[40:41]
	v_cndmask_b32_e64 v84, v102, v86, s[40:41]
	v_cndmask_b32_e64 v37, v69, v83, s[38:39]
	v_pk_fma_f32 v[40:41], v[40:41], v[84:85], v[42:43]
	s_nop 0
	v_pk_fma_f32 v[36:37], v[38:39], v[36:37], v[40:41]
	s_nop 0
	v_pk_fma_f32 v[34:35], v[50:51], v[34:35], v[36:37]
	s_nop 0
	v_mul_f32_e32 v36, 0xbfb8aa3b, v35
	v_exp_f32_e32 v36, v36
	s_nop 0
	v_add_f32_e32 v36, 1.0, v36
	v_rcp_f32_e32 v36, v36
	s_nop 0
	v_mul_f32_e32 v35, v35, v36
	v_mul_f32_e32 v42, v34, v35
	s_waitcnt vmcnt(0)
; __device__ __forceinline__ float sigmoidf_(float x) { return __builtin_amdgcn_rcpf(1.0f + __expf(-x)); }
; template <int N> __device__ __forceinline__ float dpp_ror(float v) { return __builtin_bit_cast(float, __builtin_amdgcn_update_dpp(0, __builtin_bit_cast(int, v), 0x120 + N, 0xf, 0xf, false)); }
;     __device__ __forceinline__ void operator()(Acc& acc, const Unit& u, int wr, int wc, int fr, int fq) const {
;     ...
;             for (int i = 0; i < 4; ++i) {
;                 const int cg_ = ch0 + 4 * n + i, cv_ = DFF + cg_;
;                 const float g0 = cw[cg_], g1 = cw[NUP + cg_], g2 = cw[2 * NUP + cg_], gb = cb[cg_];
;                 const float v0 = cw[cv_], v1 = cw[NUP + cv_], v2 = cw[2 * NUP + cv_], vb = cb[cv_];
;                 float pg1 = 0.f, pg2 = 0.f, pv1 = 0.f, pv2 = 0.f;
; #pragma unroll
;                 for (int q = 0; q < 8; ++q) {
;                     float cgv = acc[q >> 2][0][q & 3][n][i], cvv = acc[q >> 2][1][q & 3][n][i];
;                     asm volatile("" : "+v"(cgv), "+v"(cvv) : "v"(chain));
;                     const float tg1 = dpp_ror<1>(cgv), tg2 = dpp_ror<2>(cgv), tv1 = dpp_ror<1>(cvv), tv2 = dpp_ror<2>(cvv);
;                     const float sg1 = fr >= 1 ? tg1 : pg1, sg2 = fr >= 2 ? tg2 : pg2, sv1 = fr >= 1 ? tv1 : pv1, sv2 = fr >= 2 ? tv2 : pv2;
;                     const float gg = gb + g0 * sg2 + g1 * sg1 + g2 * cgv;
;                     const float vv = vb + v0 * sv2 + v1 * sv1 + v2 * cvv;
;                     chain = gg * sigmoidf_(gg) * vv; acc[q >> 2][0][q & 3][n][i] = chain;
;                     pg1 = tg1; pg2 = tg2; pv1 = tv1; pv2 = tv2;
;                 }
	v_mov_b32_e32 v37, v232
	v_mov_b32_e32 v35, v233
	v_mov_b32_e32 v34, v234
	v_mov_b32_e32 v39, v235
	v_mov_b32_e32 v38, v236
	v_mov_b32_e32 v36, v237
	v_mov_b32_e32 v51, v238
	v_mov_b32_e32 v50, v239
	global_load_dword v240, v[6:7], off offset:24
	global_load_dword v241, v[8:9], off offset:2072
	global_load_dword v242, v[10:11], off offset:24
	global_load_dword v243, v[16:17], off offset:24
	global_load_dword v244, v[20:21], off offset:3096
	global_load_dword v245, v[18:19], off offset:3096
	global_load_dword v246, v[22:23], off offset:1048
	global_load_dword v247, v[24:25], off offset:3096
	v_mov_b32_dpp v69, v126 row_ror:1 row_mask:0xf bank_mask:0xf
	v_mov_b32_dpp v83, v126 row_ror:2 row_mask:0xf bank_mask:0xf
	v_cndmask_b32_e64 v127, v69, 0, s[38:39]
	v_cndmask_b32_e64 v40, 0, v83, s[40:41]
	v_mov_b32_dpp v86, v128 row_ror:1 row_mask:0xf bank_mask:0xf
	v_cndmask_b32_e64 v129, v86, 0, s[38:39]
	v_mov_b32_dpp v87, v128 row_ror:2 row_mask:0xf bank_mask:0xf
	v_cndmask_b32_e64 v43, 0, v87, s[40:41]
	s_nop 0
	v_fma_f32 v84, v37, v40, v39
	v_pk_mul_f32 v[40:41], v[34:35], v[126:127]
	s_nop 0
	v_fma_f32 v43, v36, v43, v38
	v_add_f32_e32 v41, v41, v84
	v_add_f32_e32 v105, v40, v41
	v_mul_f32_e32 v40, 0xbfb8aa3b, v105
	v_exp_f32_e32 v111, v40
	v_mov_b32_e32 v41, v34
	s_nop 0
	v_pk_mul_f32 v[84:85], v[50:51], v[128:129]
	v_mov_b32_e32 v40, v50
	v_add_f32_e32 v34, 1.0, v111
	v_rcp_f32_e32 v50, v34
	v_add_f32_e32 v43, v85, v43
	v_add_f32_e32 v43, v84, v43
	v_mov_b32_e32 v34, v51
	v_mul_f32_e32 v50, v105, v50
	v_mul_f32_e32 v43, v43, v50
	v_mov_b32_dpp v101, v117 row_ror:2 row_mask:0xf bank_mask:0xf
	v_mov_b32_dpp v103, v116 row_ror:2 row_mask:0xf bank_mask:0xf
	v_mov_b32_dpp v100, v117 row_ror:1 row_mask:0xf bank_mask:0xf
	v_mov_b32_dpp v102, v116 row_ror:1 row_mask:0xf bank_mask:0xf
	v_cndmask_b32_e64 v85, v83, v101, s[40:41]
	v_cndmask_b32_e64 v84, v87, v103, s[40:41]
	v_cndmask_b32_e64 v51, v100, v69, s[38:39]
	v_cndmask_b32_e64 v50, v102, v86, s[38:39]
	v_pk_fma_f32 v[84:85], v[36:37], v[84:85], v[38:39]
	v_pk_fma_f32 v[50:51], v[34:35], v[50:51], v[84:85]
	s_nop 0
	v_pk_fma_f32 v[50:51], v[40:41], v[116:117], v[50:51]
	s_nop 0
	v_mul_f32_e32 v69, 0xbfb8aa3b, v51
	v_exp_f32_e32 v69, v69
	s_nop 0
	v_add_f32_e32 v69, 1.0, v69
	v_rcp_f32_e32 v69, v69
	s_nop 0
	v_mul_f32_e32 v51, v51, v69
	v_mul_f32_e32 v50, v50, v51
	v_mov_b32_dpp v105, v97 row_ror:2 row_mask:0xf bank_mask:0xf
	v_mov_b32_dpp v115, v96 row_ror:2 row_mask:0xf bank_mask:0xf
	v_mov_b32_dpp v83, v97 row_ror:1 row_mask:0xf bank_mask:0xf
	v_mov_b32_dpp v111, v96 row_ror:1 row_mask:0xf bank_mask:0xf
	v_cndmask_b32_e64 v87, v101, v105, s[40:41]
	v_cndmask_b32_e64 v86, v103, v115, s[40:41]
	v_cndmask_b32_e64 v85, v83, v100, s[38:39]
	v_cndmask_b32_e64 v84, v111, v102, s[38:39]
	v_pk_fma_f32 v[86:87], v[36:37], v[86:87], v[38:39]
	v_pk_fma_f32 v[84:85], v[34:35], v[84:85], v[86:87]
	v_pk_fma_f32 v[84:85], v[40:41], v[96:97], v[84:85]
	v_mul_f32_e32 v51, 0xbfb8aa3b, v85
	v_exp_f32_e32 v51, v51
	s_nop 0
	v_add_f32_e32 v51, 1.0, v51
	v_rcp_f32_e32 v51, v51
	s_nop 0
	v_mul_f32_e32 v51, v85, v51
	v_mul_f32_e32 v51, v84, v51
	v_mov_b32_dpp v97, v81 row_ror:2 row_mask:0xf bank_mask:0xf
	v_mov_b32_dpp v101, v80 row_ror:2 row_mask:0xf bank_mask:0xf
	v_mov_b32_dpp v96, v81 row_ror:1 row_mask:0xf bank_mask:0xf
	v_mov_b32_dpp v100, v80 row_ror:1 row_mask:0xf bank_mask:0xf
	v_cndmask_b32_e64 v87, v105, v97, s[40:41]
	v_cndmask_b32_e64 v86, v115, v101, s[40:41]
	v_cndmask_b32_e64 v85, v96, v83, s[38:39]
	v_cndmask_b32_e64 v84, v100, v111, s[38:39]
	v_pk_fma_f32 v[86:87], v[36:37], v[86:87], v[38:39]
	v_pk_fma_f32 v[84:85], v[34:35], v[84:85], v[86:87]
	v_pk_fma_f32 v[80:81], v[40:41], v[80:81], v[84:85]
	v_mul_f32_e32 v69, 0xbfb8aa3b, v81
	v_exp_f32_e32 v69, v69
	s_nop 0
	v_add_f32_e32 v69, 1.0, v69
	v_rcp_f32_e32 v69, v69
	s_nop 0
	v_mul_f32_e32 v69, v81, v69
	v_mul_f32_e32 v69, v80, v69
	v_mov_b32_dpp v86, v67 row_ror:2 row_mask:0xf bank_mask:0xf
	v_mov_b32_dpp v102, v66 row_ror:2 row_mask:0xf bank_mask:0xf
	v_mov_b32_dpp v83, v67 row_ror:1 row_mask:0xf bank_mask:0xf
	v_mov_b32_dpp v87, v66 row_ror:1 row_mask:0xf bank_mask:0xf
	v_cndmask_b32_e64 v85, v97, v86, s[40:41]
	v_cndmask_b32_e64 v84, v101, v102, s[40:41]
	v_cndmask_b32_e64 v81, v83, v96, s[38:39]
	v_cndmask_b32_e64 v80, v87, v100, s[38:39]
	v_pk_fma_f32 v[84:85], v[36:37], v[84:85], v[38:39]
	v_pk_fma_f32 v[80:81], v[34:35], v[80:81], v[84:85]
	v_pk_fma_f32 v[66:67], v[40:41], v[66:67], v[80:81]
	v_mul_f32_e32 v80, 0xbfb8aa3b, v67
	v_exp_f32_e32 v80, v80
	s_nop 0
	v_add_f32_e32 v80, 1.0, v80
	v_rcp_f32_e32 v80, v80
	s_nop 0
	v_mul_f32_e32 v67, v67, v80
	v_mul_f32_e32 v66, v66, v67
	v_mov_b32_dpp v97, v49 row_ror:2 row_mask:0xf bank_mask:0xf
	v_mov_b32_dpp v101, v48 row_ror:2 row_mask:0xf bank_mask:0xf
	v_mov_b32_dpp v96, v49 row_ror:1 row_mask:0xf bank_mask:0xf
	v_mov_b32_dpp v100, v48 row_ror:1 row_mask:0xf bank_mask:0xf
	v_cndmask_b32_e64 v85, v86, v97, s[40:41]
	v_cndmask_b32_e64 v84, v102, v101, s[40:41]
	v_cndmask_b32_e64 v81, v96, v83, s[38:39]
	v_cndmask_b32_e64 v80, v100, v87, s[38:39]
	v_pk_fma_f32 v[84:85], v[36:37], v[84:85], v[38:39]
	v_pk_fma_f32 v[80:81], v[34:35], v[80:81], v[84:85]
	v_pk_fma_f32 v[48:49], v[40:41], v[48:49], v[80:81]
	v_mul_f32_e32 v67, 0xbfb8aa3b, v49
	v_exp_f32_e32 v67, v67
	s_nop 0
	v_add_f32_e32 v67, 1.0, v67
	v_rcp_f32_e32 v67, v67
	s_nop 0
	v_mul_f32_e32 v49, v49, v67
	v_mul_f32_e32 v48, v48, v49
	v_mov_b32_dpp v86, v33 row_ror:2 row_mask:0xf bank_mask:0xf
	v_mov_b32_dpp v102, v32 row_ror:2 row_mask:0xf bank_mask:0xf
	v_mov_b32_dpp v83, v33 row_ror:1 row_mask:0xf bank_mask:0xf
	v_mov_b32_dpp v87, v32 row_ror:1 row_mask:0xf bank_mask:0xf
	v_cndmask_b32_e64 v85, v97, v86, s[40:41]
	v_cndmask_b32_e64 v84, v101, v102, s[40:41]
	v_cndmask_b32_e64 v81, v83, v96, s[38:39]
	v_cndmask_b32_e64 v80, v87, v100, s[38:39]
	v_pk_fma_f32 v[84:85], v[36:37], v[84:85], v[38:39]
	s_nop 0
	v_pk_fma_f32 v[80:81], v[34:35], v[80:81], v[84:85]
	v_pk_fma_f32 v[32:33], v[40:41], v[32:33], v[80:81]
	v_mul_f32_e32 v49, 0xbfb8aa3b, v33
	v_exp_f32_e32 v49, v49
	s_nop 0
	v_add_f32_e32 v49, 1.0, v49
	v_rcp_f32_e32 v49, v49
	s_nop 0
	v_mul_f32_e32 v33, v33, v49
	v_mul_f32_e32 v49, v32, v33
	v_mov_b32_dpp v80, v27 row_ror:2 row_mask:0xf bank_mask:0xf
	v_mov_b32_dpp v81, v26 row_ror:1 row_mask:0xf bank_mask:0xf
	v_mov_b32_dpp v84, v26 row_ror:2 row_mask:0xf bank_mask:0xf
	v_mov_b32_dpp v67, v27 row_ror:1 row_mask:0xf bank_mask:0xf
	v_cndmask_b32_e64 v32, v81, v87, s[38:39]
	v_cndmask_b32_e64 v81, v86, v80, s[40:41]
	v_cndmask_b32_e64 v80, v102, v84, s[40:41]
	v_cndmask_b32_e64 v33, v67, v83, s[38:39]
	v_pk_fma_f32 v[36:37], v[36:37], v[80:81], v[38:39]
	s_nop 0
	v_pk_fma_f32 v[32:33], v[34:35], v[32:33], v[36:37]
	s_nop 0
	v_pk_fma_f32 v[26:27], v[40:41], v[26:27], v[32:33]
	s_nop 0
	v_mul_f32_e32 v32, 0xbfb8aa3b, v27
	v_exp_f32_e32 v32, v32
	s_nop 0
	v_add_f32_e32 v32, 1.0, v32
	v_rcp_f32_e32 v32, v32
	s_nop 0
	v_mul_f32_e32 v27, v27, v32
	v_mul_f32_e32 v38, v26, v27
	s_waitcnt vmcnt(0)
; __device__ __forceinline__ float sigmoidf_(float x) { return __builtin_amdgcn_rcpf(1.0f + __expf(-x)); }
; template <int N> __device__ __forceinline__ float dpp_ror(float v) { return __builtin_bit_cast(float, __builtin_amdgcn_update_dpp(0, __builtin_bit_cast(int, v), 0x120 + N, 0xf, 0xf, false)); }
;     __device__ __forceinline__ void operator()(Acc& acc, const Unit& u, int wr, int wc, int fr, int fq) const {
;     ...
;             for (int i = 0; i < 4; ++i) {
;                 const int cg_ = ch0 + 4 * n + i, cv_ = DFF + cg_;
;                 const float g0 = cw[cg_], g1 = cw[NUP + cg_], g2 = cw[2 * NUP + cg_], gb = cb[cg_];
;                 const float v0 = cw[cv_], v1 = cw[NUP + cv_], v2 = cw[2 * NUP + cv_], vb = cb[cv_];
;                 float pg1 = 0.f, pg2 = 0.f, pv1 = 0.f, pv2 = 0.f;
; #pragma unroll
;                 for (int q = 0; q < 8; ++q) {
;                     float cgv = acc[q >> 2][0][q & 3][n][i], cvv = acc[q >> 2][1][q & 3][n][i];
;                     asm volatile("" : "+v"(cgv), "+v"(cvv) : "v"(chain));
;                     const float tg1 = dpp_ror<1>(cgv), tg2 = dpp_ror<2>(cgv), tv1 = dpp_ror<1>(cvv), tv2 = dpp_ror<2>(cvv);
;                     const float sg1 = fr >= 1 ? tg1 : pg1, sg2 = fr >= 2 ? tg2 : pg2, sv1 = fr >= 1 ? tv1 : pv1, sv2 = fr >= 2 ? tv2 : pv2;
;                     const float gg = gb + g0 * sg2 + g1 * sg1 + g2 * cgv;
;                     const float vv = vb + v0 * sv2 + v1 * sv1 + v2 * cvv;
;                     chain = gg * sigmoidf_(gg) * vv; acc[q >> 2][0][q & 3][n][i] = chain;
;                     pg1 = tg1; pg2 = tg2; pv1 = tv1; pv2 = tv2;
;                 }
	v_mov_b32_e32 v33, v240
	v_mov_b32_e32 v27, v241
	v_mov_b32_e32 v26, v242
	v_mov_b32_e32 v35, v243
	v_mov_b32_e32 v34, v244
	v_mov_b32_e32 v32, v245
	v_mov_b32_e32 v41, v246
	v_mov_b32_e32 v40, v247
	global_load_dword v232, v[6:7], off offset:28
	global_load_dword v233, v[8:9], off offset:2076
	global_load_dword v234, v[10:11], off offset:28
	global_load_dword v235, v[16:17], off offset:28
	global_load_dword v236, v[18:19], off offset:3100
	global_load_dword v237, v[22:23], off offset:1052
	global_load_dword v238, v[24:25], off offset:3100
	global_load_dword v239, v[20:21], off offset:3100
	v_mov_b32_dpp v67, v122 row_ror:1 row_mask:0xf bank_mask:0xf
	v_mov_b32_dpp v83, v122 row_ror:2 row_mask:0xf bank_mask:0xf
	v_cndmask_b32_e64 v123, v67, 0, s[38:39]
	v_cndmask_b32_e64 v36, 0, v83, s[40:41]
	v_mov_b32_dpp v84, v124 row_ror:1 row_mask:0xf bank_mask:0xf
	v_cndmask_b32_e64 v125, v84, 0, s[38:39]
	v_mov_b32_dpp v85, v124 row_ror:2 row_mask:0xf bank_mask:0xf
	v_cndmask_b32_e64 v39, 0, v85, s[40:41]
	s_nop 0
	v_fma_f32 v80, v33, v36, v35
	v_pk_mul_f32 v[36:37], v[26:27], v[122:123]
	s_nop 0
	v_fma_f32 v39, v32, v39, v34
	v_add_f32_e32 v37, v37, v80
	v_add_f32_e32 v100, v36, v37
	v_mul_f32_e32 v36, 0xbfb8aa3b, v100
	v_exp_f32_e32 v101, v36
	v_mov_b32_e32 v37, v26
	s_nop 0
	v_pk_mul_f32 v[80:81], v[40:41], v[124:125]
	v_mov_b32_e32 v36, v40
	v_add_f32_e32 v26, 1.0, v101
	v_rcp_f32_e32 v40, v26
	v_add_f32_e32 v39, v81, v39
	v_add_f32_e32 v39, v80, v39
	v_mov_b32_e32 v26, v41
	v_mul_f32_e32 v40, v100, v40
	v_mul_f32_e32 v39, v39, v40
	v_mov_b32_dpp v87, v113 row_ror:2 row_mask:0xf bank_mask:0xf
	v_mov_b32_dpp v97, v112 row_ror:2 row_mask:0xf bank_mask:0xf
	v_mov_b32_dpp v86, v113 row_ror:1 row_mask:0xf bank_mask:0xf
	v_mov_b32_dpp v96, v112 row_ror:1 row_mask:0xf bank_mask:0xf
	v_cndmask_b32_e64 v81, v83, v87, s[40:41]
	v_cndmask_b32_e64 v80, v85, v97, s[40:41]
	v_cndmask_b32_e64 v41, v86, v67, s[38:39]
	v_cndmask_b32_e64 v40, v96, v84, s[38:39]
	v_pk_fma_f32 v[80:81], v[32:33], v[80:81], v[34:35]
	v_pk_fma_f32 v[40:41], v[26:27], v[40:41], v[80:81]
	s_nop 0
	v_pk_fma_f32 v[40:41], v[36:37], v[112:113], v[40:41]
	s_nop 0
	v_mul_f32_e32 v67, 0xbfb8aa3b, v41
	v_exp_f32_e32 v67, v67
	s_nop 0
	v_add_f32_e32 v67, 1.0, v67
	v_rcp_f32_e32 v67, v67
	s_nop 0
	v_mul_f32_e32 v41, v41, v67
	v_mul_f32_e32 v40, v40, v41
	v_mov_b32_dpp v100, v95 row_ror:2 row_mask:0xf bank_mask:0xf
	v_mov_b32_dpp v102, v94 row_ror:2 row_mask:0xf bank_mask:0xf
	v_mov_b32_dpp v83, v95 row_ror:1 row_mask:0xf bank_mask:0xf
	v_mov_b32_dpp v101, v94 row_ror:1 row_mask:0xf bank_mask:0xf
	v_cndmask_b32_e64 v85, v87, v100, s[40:41]
	v_cndmask_b32_e64 v84, v97, v102, s[40:41]
	v_cndmask_b32_e64 v81, v83, v86, s[38:39]
	v_cndmask_b32_e64 v80, v101, v96, s[38:39]
	v_pk_fma_f32 v[84:85], v[32:33], v[84:85], v[34:35]
	v_pk_fma_f32 v[80:81], v[26:27], v[80:81], v[84:85]
	v_pk_fma_f32 v[80:81], v[36:37], v[94:95], v[80:81]
	v_mul_f32_e32 v41, 0xbfb8aa3b, v81
	v_exp_f32_e32 v41, v41
	s_nop 0
	v_add_f32_e32 v41, 1.0, v41
	v_rcp_f32_e32 v41, v41
	s_nop 0
	v_mul_f32_e32 v41, v81, v41
	v_mul_f32_e32 v41, v80, v41
	v_mov_b32_dpp v87, v79 row_ror:2 row_mask:0xf bank_mask:0xf
	v_mov_b32_dpp v95, v78 row_ror:2 row_mask:0xf bank_mask:0xf
	v_mov_b32_dpp v86, v79 row_ror:1 row_mask:0xf bank_mask:0xf
	v_mov_b32_dpp v94, v78 row_ror:1 row_mask:0xf bank_mask:0xf
	v_cndmask_b32_e64 v85, v100, v87, s[40:41]
	v_cndmask_b32_e64 v84, v102, v95, s[40:41]
	v_cndmask_b32_e64 v81, v86, v83, s[38:39]
	v_cndmask_b32_e64 v80, v94, v101, s[38:39]
	v_pk_fma_f32 v[84:85], v[32:33], v[84:85], v[34:35]
	v_pk_fma_f32 v[80:81], v[26:27], v[80:81], v[84:85]
	v_pk_fma_f32 v[78:79], v[36:37], v[78:79], v[80:81]
	v_mul_f32_e32 v67, 0xbfb8aa3b, v79
	v_exp_f32_e32 v67, v67
	s_nop 0
	v_add_f32_e32 v67, 1.0, v67
	v_rcp_f32_e32 v67, v67
	s_nop 0
	v_mul_f32_e32 v67, v79, v67
	v_mul_f32_e32 v67, v78, v67
	v_mov_b32_dpp v84, v65 row_ror:2 row_mask:0xf bank_mask:0xf
	v_mov_b32_dpp v96, v64 row_ror:2 row_mask:0xf bank_mask:0xf
	v_mov_b32_dpp v83, v65 row_ror:1 row_mask:0xf bank_mask:0xf
	v_mov_b32_dpp v85, v64 row_ror:1 row_mask:0xf bank_mask:0xf
	v_cndmask_b32_e64 v81, v87, v84, s[40:41]
	v_cndmask_b32_e64 v80, v95, v96, s[40:41]
	v_cndmask_b32_e64 v79, v83, v86, s[38:39]
	v_cndmask_b32_e64 v78, v85, v94, s[38:39]
	v_pk_fma_f32 v[80:81], v[32:33], v[80:81], v[34:35]
	v_pk_fma_f32 v[78:79], v[26:27], v[78:79], v[80:81]
	v_pk_fma_f32 v[64:65], v[36:37], v[64:65], v[78:79]
	v_mul_f32_e32 v78, 0xbfb8aa3b, v65
	v_exp_f32_e32 v78, v78
	s_nop 0
	v_add_f32_e32 v78, 1.0, v78
	v_rcp_f32_e32 v78, v78
	s_nop 0
	v_mul_f32_e32 v65, v65, v78
	v_mul_f32_e32 v64, v64, v65
	v_mov_b32_dpp v87, v47 row_ror:2 row_mask:0xf bank_mask:0xf
	v_mov_b32_dpp v95, v46 row_ror:2 row_mask:0xf bank_mask:0xf
	v_mov_b32_dpp v86, v47 row_ror:1 row_mask:0xf bank_mask:0xf
	v_mov_b32_dpp v94, v46 row_ror:1 row_mask:0xf bank_mask:0xf
	v_cndmask_b32_e64 v81, v84, v87, s[40:41]
	v_cndmask_b32_e64 v80, v96, v95, s[40:41]
	v_cndmask_b32_e64 v79, v86, v83, s[38:39]
	v_cndmask_b32_e64 v78, v94, v85, s[38:39]
	v_pk_fma_f32 v[80:81], v[32:33], v[80:81], v[34:35]
	v_pk_fma_f32 v[78:79], v[26:27], v[78:79], v[80:81]
	v_pk_fma_f32 v[46:47], v[36:37], v[46:47], v[78:79]
	v_mul_f32_e32 v65, 0xbfb8aa3b, v47
	v_exp_f32_e32 v65, v65
	s_nop 0
	v_add_f32_e32 v65, 1.0, v65
	v_rcp_f32_e32 v65, v65
	s_nop 0
	v_mul_f32_e32 v47, v47, v65
	v_mul_f32_e32 v46, v46, v47
	v_mov_b32_dpp v84, v31 row_ror:2 row_mask:0xf bank_mask:0xf
	v_mov_b32_dpp v96, v30 row_ror:2 row_mask:0xf bank_mask:0xf
	v_mov_b32_dpp v83, v31 row_ror:1 row_mask:0xf bank_mask:0xf
	v_mov_b32_dpp v85, v30 row_ror:1 row_mask:0xf bank_mask:0xf
	v_cndmask_b32_e64 v81, v87, v84, s[40:41]
	v_cndmask_b32_e64 v80, v95, v96, s[40:41]
	v_cndmask_b32_e64 v79, v83, v86, s[38:39]
	v_cndmask_b32_e64 v78, v85, v94, s[38:39]
	v_pk_fma_f32 v[80:81], v[32:33], v[80:81], v[34:35]
	v_pk_fma_f32 v[78:79], v[26:27], v[78:79], v[80:81]
	v_pk_fma_f32 v[30:31], v[36:37], v[30:31], v[78:79]
	v_mul_f32_e32 v47, 0xbfb8aa3b, v31
	v_exp_f32_e32 v47, v47
	s_nop 0
	v_add_f32_e32 v47, 1.0, v47
	v_rcp_f32_e32 v47, v47
	s_nop 0
	v_mul_f32_e32 v31, v31, v47
	v_mul_f32_e32 v30, v30, v31
	v_mov_b32_dpp v80, v15 row_ror:2 row_mask:0xf bank_mask:0xf
	v_mov_b32_dpp v86, v14 row_ror:2 row_mask:0xf bank_mask:0xf
	v_mov_b32_dpp v65, v15 row_ror:1 row_mask:0xf bank_mask:0xf
	v_mov_b32_dpp v78, v14 row_ror:1 row_mask:0xf bank_mask:0xf
	v_cndmask_b32_e64 v81, v84, v80, s[40:41]
	v_cndmask_b32_e64 v80, v96, v86, s[40:41]
	v_cndmask_b32_e64 v79, v65, v83, s[38:39]
	v_cndmask_b32_e64 v78, v78, v85, s[38:39]
	v_pk_fma_f32 v[32:33], v[32:33], v[80:81], v[34:35]
	s_nop 0
	v_pk_fma_f32 v[26:27], v[26:27], v[78:79], v[32:33]
	s_nop 0
	v_pk_fma_f32 v[14:15], v[36:37], v[14:15], v[26:27]
	s_nop 0
	v_mul_f32_e32 v26, 0xbfb8aa3b, v15
	v_exp_f32_e32 v26, v26
	s_nop 0
	v_add_f32_e32 v26, 1.0, v26
	v_rcp_f32_e32 v26, v26
	s_nop 0
	v_mul_f32_e32 v15, v15, v26
	v_mul_f32_e32 v26, v14, v15
	s_waitcnt vmcnt(0)
; __device__ __forceinline__ unsigned pk2(float lo, float hi) { const f32x2_t v = {lo, hi}; const bf16x2_t b = __builtin_convertvector(v, bf16x2_t); return __builtin_bit_cast(unsigned, b); }
; __device__ __forceinline__ float sigmoidf_(float x) { return __builtin_amdgcn_rcpf(1.0f + __expf(-x)); }
; template <int N> __device__ __forceinline__ float dpp_ror(float v) { return __builtin_bit_cast(float, __builtin_amdgcn_update_dpp(0, __builtin_bit_cast(int, v), 0x120 + N, 0xf, 0xf, false)); }
;     __device__ __forceinline__ void operator()(Acc& acc, const Unit& u, int wr, int wc, int fr, int fq) const {
;     ...
;                 for (int q = 0; q < 8; ++q) {
;                     float cgv = acc[q >> 2][0][q & 3][n][i], cvv = acc[q >> 2][1][q & 3][n][i];
;                     asm volatile("" : "+v"(cgv), "+v"(cvv) : "v"(chain));
;                     const float tg1 = dpp_ror<1>(cgv), tg2 = dpp_ror<2>(cgv), tv1 = dpp_ror<1>(cvv), tv2 = dpp_ror<2>(cvv);
;                     const float sg1 = fr >= 1 ? tg1 : pg1, sg2 = fr >= 2 ? tg2 : pg2, sv1 = fr >= 1 ? tv1 : pv1, sv2 = fr >= 2 ? tv2 : pv2;
;                     const float gg = gb + g0 * sg2 + g1 * sg1 + g2 * cgv;
;                     const float vv = vb + v0 * sv2 + v1 * sv1 + v2 * cvv;
;                     chain = gg * sigmoidf_(gg) * vv; acc[q >> 2][0][q & 3][n][i] = chain;
;                     pg1 = tg1; pg2 = tg2; pv1 = tv1; pv2 = tv2;
;                 }
;     ...
; #pragma unroll
;         for (int q = 0; q < 8; ++q) {
;             const int t = tbase + 16 * q;
;             if ((16 * q + fr >= 2) && (t < SEQ)) {
;                 const f32x4 a0 = acc[q >> 2][0][q & 3][0], a1 = acc[q >> 2][0][q & 3][1];
;                 u32x4 w; w.x = pk2(a0[0], a0[1]); w.y = pk2(a0[2], a0[3]); w.z = pk2(a1[0], a1[1]); w.w = pk2(a1[2], a1[3]);
;                 *(u32x4*)(act + (size_t)(b * SEQ + t) * DFF + ch0) = w;
	v_mov_b32_e32 v15, v232
	s_nop 0
	v_mov_b32_e32 v7, v233
	v_mov_b32_e32 v6, v234
	s_nop 0
	v_mov_b32_e32 v9, v235
	v_mov_b32_e32 v14, v236
	s_nop 0
	v_mov_b32_e32 v17, v237
	v_mov_b32_e32 v16, v238
	v_mov_b32_e32 v8, v239
	v_mov_b32_dpp v19, v120 row_ror:1 row_mask:0xf bank_mask:0xf
	v_mov_b32_dpp v22, v120 row_ror:2 row_mask:0xf bank_mask:0xf
	v_cndmask_b32_e64 v121, v19, 0, s[38:39]
	v_cndmask_b32_e64 v10, 0, v22, s[40:41]
	v_mov_b32_dpp v20, v110 row_ror:1 row_mask:0xf bank_mask:0xf
	v_mov_b32_dpp v24, v110 row_ror:2 row_mask:0xf bank_mask:0xf
	v_cndmask_b32_e64 v111, v20, 0, s[38:39]
	v_cndmask_b32_e64 v18, 0, v24, s[40:41]
	v_mov_b32_e32 v35, v3
	v_mov_b32_e32 v36, v3
	s_nop 0
	v_fma_f32 v21, v15, v10, v9
	v_pk_mul_f32 v[10:11], v[6:7], v[120:121]
	s_nop 0
	v_fma_f32 v18, v14, v18, v8
	v_add_f32_e32 v11, v11, v21
	v_add_f32_e32 v21, v10, v11
	v_pk_mul_f32 v[10:11], v[16:17], v[110:111]
	s_nop 0
	v_add_f32_e32 v11, v11, v18
	v_add_f32_e32 v10, v10, v11
	v_mul_f32_e32 v11, 0xbfb8aa3b, v21
	v_exp_f32_e32 v11, v11
	s_nop 0
	v_add_f32_e32 v11, 1.0, v11
	v_rcp_f32_e32 v11, v11
	s_nop 0
	v_mul_f32_e32 v11, v21, v11
	v_mul_f32_e32 v18, v10, v11
	v_mov_b32_e32 v11, v6
	v_mov_b32_e32 v6, v17
	v_mov_b32_dpp v27, v109 row_ror:2 row_mask:0xf bank_mask:0xf
	v_mov_b32_dpp v32, v108 row_ror:2 row_mask:0xf bank_mask:0xf
	v_mov_b32_dpp v25, v109 row_ror:1 row_mask:0xf bank_mask:0xf
	v_mov_b32_dpp v31, v108 row_ror:1 row_mask:0xf bank_mask:0xf
	v_cndmask_b32_e64 v23, v22, v27, s[40:41]
	v_cndmask_b32_e64 v22, v24, v32, s[40:41]
	v_cndmask_b32_e64 v21, v25, v19, s[38:39]
	v_cndmask_b32_e64 v20, v31, v20, s[38:39]
	v_pk_fma_f32 v[22:23], v[14:15], v[22:23], v[8:9]
	v_mov_b32_e32 v10, v16
	v_pk_fma_f32 v[16:17], v[6:7], v[20:21], v[22:23]
	v_pk_fma_f32 v[16:17], v[10:11], v[108:109], v[16:17]
	s_nop 0
	v_mul_f32_e32 v19, 0xbfb8aa3b, v17
	v_exp_f32_e32 v19, v19
	s_nop 0
	v_add_f32_e32 v19, 1.0, v19
	v_rcp_f32_e32 v19, v19
	s_nop 0
	v_mul_f32_e32 v17, v17, v19
	v_mul_f32_e32 v16, v16, v17
	v_mov_b32_dpp v24, v93 row_ror:2 row_mask:0xf bank_mask:0xf
	v_mov_b32_dpp v34, v92 row_ror:2 row_mask:0xf bank_mask:0xf
	v_mov_b32_dpp v19, v93 row_ror:1 row_mask:0xf bank_mask:0xf
	v_mov_b32_dpp v33, v92 row_ror:1 row_mask:0xf bank_mask:0xf
	v_cndmask_b32_e64 v23, v27, v24, s[40:41]
	v_cndmask_b32_e64 v22, v32, v34, s[40:41]
	v_cndmask_b32_e64 v21, v19, v25, s[38:39]
	v_cndmask_b32_e64 v20, v33, v31, s[38:39]
	v_pk_fma_f32 v[22:23], v[14:15], v[22:23], v[8:9]
	v_pk_fma_f32 v[20:21], v[6:7], v[20:21], v[22:23]
	v_pk_fma_f32 v[20:21], v[10:11], v[92:93], v[20:21]
	v_mul_f32_e32 v17, 0xbfb8aa3b, v21
	v_exp_f32_e32 v17, v17
	s_nop 0
	v_add_f32_e32 v17, 1.0, v17
	v_rcp_f32_e32 v17, v17
	s_nop 0
	v_mul_f32_e32 v17, v21, v17
	v_mul_f32_e32 v17, v20, v17
	v_mov_b32_dpp v27, v77 row_ror:2 row_mask:0xf bank_mask:0xf
	v_mov_b32_dpp v32, v76 row_ror:2 row_mask:0xf bank_mask:0xf
	v_mov_b32_dpp v25, v77 row_ror:1 row_mask:0xf bank_mask:0xf
	v_mov_b32_dpp v31, v76 row_ror:1 row_mask:0xf bank_mask:0xf
	v_cndmask_b32_e64 v23, v24, v27, s[40:41]
	v_cndmask_b32_e64 v22, v34, v32, s[40:41]
	v_cndmask_b32_e64 v21, v25, v19, s[38:39]
	v_cndmask_b32_e64 v20, v31, v33, s[38:39]
	v_pk_fma_f32 v[22:23], v[14:15], v[22:23], v[8:9]
	v_pk_fma_f32 v[20:21], v[6:7], v[20:21], v[22:23]
	v_pk_fma_f32 v[20:21], v[10:11], v[76:77], v[20:21]
	v_mul_f32_e32 v19, 0xbfb8aa3b, v21
	v_exp_f32_e32 v19, v19
	s_nop 0
	v_add_f32_e32 v19, 1.0, v19
	v_rcp_f32_e32 v19, v19
	s_nop 0
	v_mul_f32_e32 v19, v21, v19
	v_mul_f32_e32 v19, v20, v19
	v_mov_b32_dpp v33, v61 row_ror:2 row_mask:0xf bank_mask:0xf
	v_mov_b32_dpp v35, v60 row_ror:2 row_mask:0xf bank_mask:0xf
	v_mov_b32_dpp v24, v61 row_ror:1 row_mask:0xf bank_mask:0xf
	v_mov_b32_dpp v34, v60 row_ror:1 row_mask:0xf bank_mask:0xf
	v_cndmask_b32_e64 v23, v27, v33, s[40:41]
	v_cndmask_b32_e64 v22, v32, v35, s[40:41]
	v_cndmask_b32_e64 v21, v24, v25, s[38:39]
	v_cndmask_b32_e64 v20, v34, v31, s[38:39]
	v_pk_fma_f32 v[22:23], v[14:15], v[22:23], v[8:9]
	v_pk_fma_f32 v[20:21], v[6:7], v[20:21], v[22:23]
	v_pk_fma_f32 v[20:21], v[10:11], v[60:61], v[20:21]
	v_mul_f32_e32 v22, 0xbfb8aa3b, v21
	v_exp_f32_e32 v22, v22
	s_nop 0
	v_add_f32_e32 v22, 1.0, v22
	v_rcp_f32_e32 v22, v22
	s_nop 0
	v_mul_f32_e32 v21, v21, v22
	v_mul_f32_e32 v20, v20, v21
	v_mov_b32_dpp v27, v45 row_ror:1 row_mask:0xf bank_mask:0xf
	v_mov_b32_dpp v31, v45 row_ror:2 row_mask:0xf bank_mask:0xf
	v_mov_b32_dpp v36, v44 row_ror:2 row_mask:0xf bank_mask:0xf
	v_mov_b32_dpp v32, v44 row_ror:1 row_mask:0xf bank_mask:0xf
	v_cndmask_b32_e64 v23, v27, v24, s[38:39]
	v_cndmask_b32_e64 v25, v33, v31, s[40:41]
	v_cndmask_b32_e64 v24, v35, v36, s[40:41]
	v_cndmask_b32_e64 v22, v32, v34, s[38:39]
	v_pk_fma_f32 v[24:25], v[14:15], v[24:25], v[8:9]
	s_nop 0
	v_pk_fma_f32 v[22:23], v[6:7], v[22:23], v[24:25]
	v_pk_fma_f32 v[22:23], v[10:11], v[44:45], v[22:23]
	s_nop 0
	v_mul_f32_e32 v21, 0xbfb8aa3b, v23
	v_exp_f32_e32 v21, v21
	s_nop 0
	v_add_f32_e32 v21, 1.0, v21
	v_rcp_f32_e32 v21, v21
	s_nop 0
	v_mul_f32_e32 v21, v23, v21
	v_mul_f32_e32 v24, v22, v21
	v_mov_b32_dpp v22, v29 row_ror:2 row_mask:0xf bank_mask:0xf
	v_mov_b32_dpp v25, v28 row_ror:2 row_mask:0xf bank_mask:0xf
	v_mov_b32_dpp v21, v29 row_ror:1 row_mask:0xf bank_mask:0xf
	v_mov_b32_dpp v23, v28 row_ror:1 row_mask:0xf bank_mask:0xf
	v_cndmask_b32_e64 v35, v31, v22, s[40:41]
	v_cndmask_b32_e64 v34, v36, v25, s[40:41]
	v_cndmask_b32_e64 v33, v21, v27, s[38:39]
	v_cndmask_b32_e64 v32, v23, v32, s[38:39]
	v_pk_fma_f32 v[34:35], v[14:15], v[34:35], v[8:9]
	v_pk_fma_f32 v[32:33], v[6:7], v[32:33], v[34:35]
	s_nop 0
	v_pk_fma_f32 v[28:29], v[10:11], v[28:29], v[32:33]
	v_mul_f32_e32 v27, 0xbfb8aa3b, v29
	v_exp_f32_e32 v27, v27
	s_nop 0
	v_add_f32_e32 v27, 1.0, v27
	v_rcp_f32_e32 v27, v27
	s_nop 0
	v_mul_f32_e32 v27, v29, v27
	v_mul_f32_e32 v27, v28, v27
	s_nop 0
	v_mov_b32_dpp v28, v13 row_ror:1 row_mask:0xf bank_mask:0xf
	v_mov_b32_dpp v29, v13 row_ror:2 row_mask:0xf bank_mask:0xf
	v_mov_b32_dpp v31, v12 row_ror:1 row_mask:0xf bank_mask:0xf
	v_mov_b32_dpp v32, v12 row_ror:2 row_mask:0xf bank_mask:0xf
	v_cmp_gt_i32_e32 vcc, s97, v198
	s_and_b64 s[44:45], s[40:41], vcc
	s_and_saveexec_b64 s[34:35], s[44:45]
	s_cbranch_execz .LBB0_45
	v_cvt_pk_bf16_f32 v37, v39, v18
	v_add_u32_e32 v18, s20, v198
	v_mov_b64_e32 v[44:45], s[8:9]
	s_movk_i32 s21, 0x1600
	v_mad_i64_i32 v[44:45], s[44:45], v18, s21, v[44:45]
	v_cvt_pk_bf16_f32 v34, v184, v137
	v_cvt_pk_bf16_f32 v35, v99, v63
	v_cvt_pk_bf16_f32 v36, v56, v43
	v_lshl_add_u64 v[44:45], v[4:5], 1, v[44:45]
	global_store_dwordx4 v[44:45], v[34:37], off
; __device__ __forceinline__ unsigned pk2(float lo, float hi) { const f32x2_t v = {lo, hi}; const bf16x2_t b = __builtin_convertvector(v, bf16x2_t); return __builtin_bit_cast(unsigned, b); }
;     __device__ __forceinline__ void operator()(Acc& acc, const Unit& u, int wr, int wc, int fr, int fq) const {
;     ...
; #pragma unroll
;         for (int q = 0; q < 8; ++q) {
;             const int t = tbase + 16 * q;
;             if ((16 * q + fr >= 2) && (t < SEQ)) {
;                 const f32x4 a0 = acc[q >> 2][0][q & 3][0], a1 = acc[q >> 2][0][q & 3][1];
;                 u32x4 w; w.x = pk2(a0[0], a0[1]); w.y = pk2(a0[2], a0[3]); w.z = pk2(a1[0], a1[1]); w.w = pk2(a1[2], a1[3]);
;                 *(u32x4*)(act + (size_t)(b * SEQ + t) * DFF + ch0) = w;
;             }
;         }
.LBB0_45:
	s_or_b64 exec, exec, s[34:35]
	s_movk_i32 s21, 0x1ff0
	v_cmp_gt_i32_e32 vcc, s21, v198
	s_and_saveexec_b64 s[34:35], vcc
	s_cbranch_execz .LBB0_47
	v_cvt_pk_bf16_f32 v37, v40, v16
	v_add_u32_e32 v16, s20, v223
	v_mov_b64_e32 v[44:45], s[8:9]
	s_movk_i32 s21, 0x1600
	v_mad_i64_i32 v[44:45], s[44:45], v16, s21, v[44:45]
	v_cvt_pk_bf16_f32 v34, v185, v138
	v_cvt_pk_bf16_f32 v35, v114, v74
	v_cvt_pk_bf16_f32 v36, v57, v50
	v_lshl_add_u64 v[44:45], v[4:5], 1, v[44:45]
	global_store_dwordx4 v[44:45], v[34:37], off
.LBB0_47:
	s_or_b64 exec, exec, s[34:35]
	s_movk_i32 s21, 0x1fe0
	v_cmp_gt_i32_e32 vcc, s21, v198
	s_and_saveexec_b64 s[34:35], vcc
	s_cbranch_execz .LBB0_49
	v_cvt_pk_bf16_f32 v37, v41, v17
	v_add_u32_e32 v18, s20, v227
	v_mov_b64_e32 v[16:17], s[8:9]
	s_movk_i32 s21, 0x1600
	v_mad_i64_i32 v[16:17], s[44:45], v18, s21, v[16:17]
	v_cvt_pk_bf16_f32 v34, v186, v106
	v_cvt_pk_bf16_f32 v35, v104, v75
	v_cvt_pk_bf16_f32 v36, v58, v51
	v_lshl_add_u64 v[16:17], v[4:5], 1, v[16:17]
	global_store_dwordx4 v[16:17], v[34:37], off
.LBB0_49:
	s_or_b64 exec, exec, s[34:35]
	s_movk_i32 s21, 0x1fd0
	v_cmp_gt_i32_e32 vcc, s21, v198
	s_and_saveexec_b64 s[34:35], vcc
	s_cbranch_execz .LBB0_51
	v_add_u32_e32 v33, s20, v226
	v_mov_b64_e32 v[34:35], s[8:9]
	s_movk_i32 s21, 0x1600
	v_mad_i64_i32 v[34:35], s[44:45], v33, s21, v[34:35]
	v_cvt_pk_bf16_f32 v16, v187, v90
	v_cvt_pk_bf16_f32 v17, v88, v82
	v_cvt_pk_bf16_f32 v18, v59, v69
	v_cvt_pk_bf16_f32 v19, v67, v19
	v_lshl_add_u64 v[34:35], v[4:5], 1, v[34:35]
	global_store_dwordx4 v[34:35], v[16:19], off
.LBB0_51:
	s_or_b64 exec, exec, s[34:35]
	s_movk_i32 s21, 0x1fc0
	v_cmp_gt_i32_e32 vcc, s21, v198
	s_and_saveexec_b64 s[34:35], vcc
	s_cbranch_execz .LBB0_53
	v_cvt_pk_bf16_f32 v19, v64, v20
	v_add_u32_e32 v20, s20, v225
	v_mov_b64_e32 v[34:35], s[8:9]
	s_movk_i32 s21, 0x1600
	v_mad_i64_i32 v[34:35], s[44:45], v20, s21, v[34:35]
	v_cvt_pk_bf16_f32 v16, v190, v91
	v_cvt_pk_bf16_f32 v17, v72, v70
	v_cvt_pk_bf16_f32 v18, v68, v66
	v_lshl_add_u64 v[34:35], v[4:5], 1, v[34:35]
	global_store_dwordx4 v[34:35], v[16:19], off
.LBB0_53:
	s_or_b64 exec, exec, s[34:35]
	s_movk_i32 s21, 0x1fb0
	v_cmp_gt_i32_e32 vcc, s21, v198
	s_and_saveexec_b64 s[34:35], vcc
	s_cbranch_execz .LBB0_55
	v_add_u32_e32 v20, s20, v224
	v_mov_b64_e32 v[34:35], s[8:9]
	s_movk_i32 s21, 0x1600
	v_mad_i64_i32 v[34:35], s[44:45], v20, s21, v[34:35]
	v_cvt_pk_bf16_f32 v16, v191, v107
	v_cvt_pk_bf16_f32 v17, v73, v55
	v_cvt_pk_bf16_f32 v18, v52, v48
	v_cvt_pk_bf16_f32 v19, v46, v24
	v_lshl_add_u64 v[34:35], v[4:5], 1, v[34:35]
	global_store_dwordx4 v[34:35], v[16:19], off
.LBB0_55:
	s_or_b64 exec, exec, s[34:35]
	s_movk_i32 s21, 0x1fa0
	v_cmp_gt_i32_e32 vcc, s21, v198
	s_and_saveexec_b64 s[34:35], vcc
	s_cbranch_execz .LBB0_57
	v_add_u32_e32 v20, s20, v222
	v_mov_b64_e32 v[34:35], s[8:9]
	s_movk_i32 s21, 0x1600
	v_mad_i64_i32 v[34:35], s[44:45], v20, s21, v[34:35]
	v_cvt_pk_bf16_f32 v16, v192, v139
	v_cvt_pk_bf16_f32 v17, v89, v71
	v_cvt_pk_bf16_f32 v18, v53, v49
	v_cvt_pk_bf16_f32 v19, v30, v27
	v_lshl_add_u64 v[34:35], v[4:5], 1, v[34:35]
	global_store_dwordx4 v[34:35], v[16:19], off
.LBB0_57:
	s_or_b64 exec, exec, s[34:35]
	s_movk_i32 s21, 0x1f90
	v_cmp_gt_i32_e32 vcc, s21, v198
	s_and_saveexec_b64 s[34:35], vcc
	s_cbranch_execz .LBB0_59
	v_cndmask_b32_e64 v19, v22, v29, s[40:41]
	v_cndmask_b32_e64 v18, v25, v32, s[40:41]
	v_cndmask_b32_e64 v17, v28, v21, s[38:39]
	v_cndmask_b32_e64 v16, v31, v23, s[38:39]
	v_pk_fma_f32 v[8:9], v[14:15], v[18:19], v[8:9]
	s_nop 0
	v_pk_fma_f32 v[6:7], v[6:7], v[16:17], v[8:9]
	v_cvt_pk_bf16_f32 v8, v42, v38
	v_pk_fma_f32 v[10:11], v[10:11], v[12:13], v[6:7]
	v_add_u32_e32 v12, s20, v199
	v_mul_f32_e32 v6, 0xbfb8aa3b, v11
	v_exp_f32_e32 v6, v6
	s_movk_i32 s20, 0x1600
	v_cvt_pk_bf16_f32 v7, v62, v54
	v_add_f32_e32 v6, 1.0, v6
	v_rcp_f32_e32 v9, v6
	v_cvt_pk_bf16_f32 v6, v136, v98
	v_mul_f32_e32 v9, v11, v9
	v_mul_f32_e32 v9, v10, v9
	v_mov_b64_e32 v[10:11], s[8:9]
	v_mad_i64_i32 v[10:11], s[20:21], v12, s20, v[10:11]
	v_cvt_pk_bf16_f32 v9, v26, v9
	v_lshl_add_u64 v[4:5], v[4:5], 1, v[10:11]
	global_store_dwordx4 v[4:5], v[6:9], off

; __device__ __forceinline__ unsigned pk2(float lo, float hi) { const f32x2_t v = {lo, hi}; const bf16x2_t b = __builtin_convertvector(v, bf16x2_t); return __builtin_bit_cast(unsigned, b); }
; __device__ __forceinline__ float bperm_f(int src_lane, float v) { return __builtin_bit_cast(float, __builtin_amdgcn_ds_bpermute(src_lane << 2, __builtin_bit_cast(int, v))); }
;     __device__ __forceinline__ void operator()(Acc& acc, const Unit& u, int wr, int wc, int fr, int fq) const {
;         const int row0 = u.pm * 256 + wr * 64 + fr, col0 = u.pn * 256 + wc * 32 + 8 * fq, ln = (fq << 4) | fr;
;         f32x4 pq[8];
; #pragma unroll
;         for (int q = 0; q < 8; ++q) pq[q] = *(const f32x4*)(ssq + (size_t)(row0 + (q >> 2) * 128 + (q & 3) * 16) * 16 + 4 * fq);
; #pragma unroll
;         for (int ai = 0; ai < 2; ++ai)
; #pragma unroll
;             for (int m = 0; m < 4; ++m) {
;                 const int row = row0 + ai * 128 + m * 16; const f32x4 p = pq[ai * 4 + m];
;                 float sq = (p[0] + p[1]) + (p[2] + p[3]); sq += bperm_f(ln ^ 16, sq); sq += bperm_f(ln ^ 32, sq);
;                 const float rs = rsqrtf(sq * (1.0f / DM) + EPS);
;                 bf16_t* rowp = O + (size_t)row * NIN + col0;
; #pragma unroll
;                 for (int bj = 0; bj < 2; ++bj) { const f32x4 v0 = acc[ai][bj][m][0] * rs, v1 = acc[ai][bj][m][1] * rs;
;                     u32x4 w; w.x = pk2(v0[0], v0[1]); w.y = pk2(v0[2], v0[3]); w.z = pk2(v1[0], v1[1]); w.w = pk2(v1[2], v1[3]);
;                     *(u32x4*)(rowp + bj * 128) = w; }
.LBB0_837:
	v_lshl_add_u32 v188, s52, 8, v169
	v_ashrrev_i32_e32 v189, 31, v188
	v_lshlrev_b64 v[100:101], 6, v[188:189]
	v_lshl_add_u64 v[100:101], v[162:163], 0, v[100:101]
	v_or_b32_e32 v196, 16, v188
	global_load_dwordx4 v[180:183], v[100:101], off
	v_ashrrev_i32_e32 v197, 31, v196
	v_lshlrev_b64 v[100:101], 6, v[196:197]
	v_lshl_add_u64 v[100:101], v[162:163], 0, v[100:101]
	global_load_dwordx4 v[224:227], v[100:101], off
	v_or_b32_e32 v194, 32, v188
	v_ashrrev_i32_e32 v195, 31, v194
	v_lshlrev_b64 v[100:101], 6, v[194:195]
	v_or_b32_e32 v192, 48, v188
	v_lshl_add_u64 v[100:101], v[162:163], 0, v[100:101]
	v_ashrrev_i32_e32 v193, 31, v192
	global_load_dwordx4 v[152:155], v[100:101], off
	v_lshlrev_b64 v[100:101], 6, v[192:193]
	v_lshl_add_u64 v[100:101], v[162:163], 0, v[100:101]
	global_load_dwordx4 v[148:151], v[100:101], off
	v_add_u32_e32 v190, 0x80, v188
	v_ashrrev_i32_e32 v191, 31, v190
	v_lshl_or_b32 v228, s51, 8, v222
	v_lshlrev_b64 v[100:101], 6, v[190:191]
	v_add_u32_e32 v186, 0x90, v188
	v_ashrrev_i32_e32 v229, 31, v228
	v_lshl_add_u64 v[100:101], v[162:163], 0, v[100:101]
	v_ashrrev_i32_e32 v187, 31, v186
	v_add_u32_e32 v184, 0xa0, v188
	v_add_u32_e32 v178, 0xb0, v188
	global_load_dwordx4 v[128:131], v[100:101], off
	v_lshlrev_b64 v[100:101], 6, v[186:187]
	v_lshl_add_u64 v[100:101], v[162:163], 0, v[100:101]
	global_load_dwordx4 v[124:127], v[100:101], off
	v_ashrrev_i32_e32 v185, 31, v184
	v_lshlrev_b64 v[100:101], 6, v[184:185]
	s_mov_b32 s42, 0x3a800000
	v_lshl_add_u64 v[100:101], v[162:163], 0, v[100:101]
	v_ashrrev_i32_e32 v179, 31, v178
	global_load_dwordx4 v[104:107], v[100:101], off
	v_lshlrev_b64 v[100:101], 6, v[178:179]
	v_lshl_add_u64 v[100:101], v[162:163], 0, v[100:101]
	global_load_dwordx4 v[100:103], v[100:101], off
	s_waitcnt vmcnt(0) lgkmcnt(0)
	v_mov_b32_e32 v230, v181
	v_mov_b32_e32 v231, v182
	v_mov_b32_e32 v181, v183
	v_pk_add_f32 v[230:231], v[230:231], v[180:181]
	v_mov_b64_e32 v[180:181], s[8:9]
	v_mad_i64_i32 v[188:189], s[40:41], v188, s72, v[180:181]
	v_lshlrev_b64 v[182:183], 1, v[228:229]
	v_lshl_add_u64 v[228:229], v[188:189], 0, v[182:183]
	v_mov_b32_e32 v188, v225
	v_mov_b32_e32 v189, v226
	v_mov_b32_e32 v225, v227
	v_pk_add_f32 v[188:189], v[188:189], v[224:225]
	v_mov_b32_e32 v225, v230
	v_mov_b32_e32 v224, v188
	v_mov_b32_e32 v230, v189
	v_pk_add_f32 v[188:189], v[224:225], v[230:231]
	ds_bpermute_b32 v225, v2, v189
	ds_bpermute_b32 v224, v2, v188
	s_mov_b32 s40, 0x358637bd
	s_waitcnt lgkmcnt(0)
	v_pk_add_f32 v[188:189], v[188:189], v[224:225]
	ds_bpermute_b32 v225, v199, v189
	ds_bpermute_b32 v224, v199, v188
	s_waitcnt lgkmcnt(0)
	v_pk_add_f32 v[224:225], v[188:189], v[224:225]
	v_mov_b64_e32 v[188:189], s[40:41]
	v_pk_fma_f32 v[224:225], v[224:225], s[42:43], v[188:189] op_sel_hi:[1,0,0]
	s_nop 0
	v_mul_f32_e32 v179, 0x4b800000, v225
	v_cmp_gt_f32_e64 s[40:41], s29, v225
	v_cmp_gt_f32_e32 vcc, s29, v224
	s_nop 0
	v_cndmask_b32_e64 v179, v225, v179, s[40:41]
	v_rsq_f32_e32 v179, v179
	s_nop 0
	v_mul_f32_e32 v185, 0x45800000, v179
	v_cndmask_b32_e64 v226, v179, v185, s[40:41]
	v_pk_mul_f32 v[146:147], v[146:147], v[226:227] op_sel_hi:[1,0]
	v_pk_mul_f32 v[144:145], v[144:145], v[226:227] op_sel_hi:[1,0]
	v_pk_mul_f32 v[230:231], v[142:143], v[226:227] op_sel_hi:[1,0]
	v_pk_mul_f32 v[142:143], v[140:141], v[226:227] op_sel_hi:[1,0]
	v_cvt_pk_bf16_f32 v140, v144, v145
	v_cvt_pk_bf16_f32 v141, v146, v147
	v_cvt_pk_bf16_f32 v142, v142, v143
	v_cvt_pk_bf16_f32 v143, v230, v231
	global_store_dwordx4 v[228:229], v[140:143], off
	v_pk_mul_f32 v[138:139], v[138:139], v[226:227] op_sel_hi:[1,0]
	v_pk_mul_f32 v[136:137], v[136:137], v[226:227] op_sel_hi:[1,0]
	v_pk_mul_f32 v[140:141], v[134:135], v[226:227] op_sel_hi:[1,0]
	v_pk_mul_f32 v[134:135], v[132:133], v[226:227] op_sel_hi:[1,0]
	v_cvt_pk_bf16_f32 v132, v136, v137
	v_cvt_pk_bf16_f32 v133, v138, v139
	v_cvt_pk_bf16_f32 v134, v134, v135
	v_cvt_pk_bf16_f32 v135, v140, v141
	global_store_dwordx4 v[228:229], v[132:135], off offset:256
	s_nop 1
	v_mul_f32_e32 v132, 0x4b800000, v224
	v_cndmask_b32_e32 v132, v224, v132, vcc
	v_rsq_f32_e32 v132, v132
	v_mad_i64_i32 v[134:135], s[40:41], v196, s72, v[180:181]
	v_lshl_add_u64 v[134:135], v[134:135], 0, v[182:183]
	v_mul_f32_e32 v133, 0x45800000, v132
	v_cndmask_b32_e32 v132, v132, v133, vcc
	v_pk_mul_f32 v[122:123], v[122:123], v[132:133] op_sel_hi:[1,0]
	v_pk_mul_f32 v[120:121], v[120:121], v[132:133] op_sel_hi:[1,0]
	v_pk_mul_f32 v[136:137], v[118:119], v[132:133] op_sel_hi:[1,0]
	v_pk_mul_f32 v[118:119], v[116:117], v[132:133] op_sel_hi:[1,0]
	v_cvt_pk_bf16_f32 v116, v120, v121
	v_cvt_pk_bf16_f32 v117, v122, v123
	v_cvt_pk_bf16_f32 v118, v118, v119
	v_cvt_pk_bf16_f32 v119, v136, v137
	global_store_dwordx4 v[134:135], v[116:119], off
	v_pk_mul_f32 v[114:115], v[114:115], v[132:133] op_sel_hi:[1,0]
	v_pk_mul_f32 v[112:113], v[112:113], v[132:133] op_sel_hi:[1,0]
	v_pk_mul_f32 v[116:117], v[110:111], v[132:133] op_sel_hi:[1,0]
	v_pk_mul_f32 v[110:111], v[108:109], v[132:133] op_sel_hi:[1,0]
	v_cvt_pk_bf16_f32 v108, v112, v113
	v_cvt_pk_bf16_f32 v109, v114, v115
	v_cvt_pk_bf16_f32 v110, v110, v111
	v_cvt_pk_bf16_f32 v111, v116, v117
	global_store_dwordx4 v[134:135], v[108:111], off offset:256
	v_mov_b32_e32 v112, v149
	v_mov_b32_e32 v113, v150
	v_mov_b32_e32 v108, v153
	v_mov_b32_e32 v109, v154
	v_mov_b32_e32 v153, v155
	v_mov_b32_e32 v149, v151
	v_pk_add_f32 v[108:109], v[108:109], v[152:153]
	v_pk_add_f32 v[112:113], v[112:113], v[148:149]
	v_mov_b32_e32 v115, v108
	v_mov_b32_e32 v114, v112
	v_mov_b32_e32 v108, v113
	v_pk_add_f32 v[108:109], v[114:115], v[108:109]
	ds_bpermute_b32 v113, v2, v109
	ds_bpermute_b32 v112, v2, v108
	v_mad_i64_i32 v[110:111], s[40:41], v194, s72, v[180:181]
	v_lshl_add_u64 v[110:111], v[110:111], 0, v[182:183]
	s_waitcnt lgkmcnt(0)
; __device__ __forceinline__ unsigned pk2(float lo, float hi) { const f32x2_t v = {lo, hi}; const bf16x2_t b = __builtin_convertvector(v, bf16x2_t); return __builtin_bit_cast(unsigned, b); }
; __device__ __forceinline__ float bperm_f(int src_lane, float v) { return __builtin_bit_cast(float, __builtin_amdgcn_ds_bpermute(src_lane << 2, __builtin_bit_cast(int, v))); }
;     __device__ __forceinline__ void operator()(Acc& acc, const Unit& u, int wr, int wc, int fr, int fq) const {
;     ...
;         for (int ai = 0; ai < 2; ++ai)
; #pragma unroll
;             for (int m = 0; m < 4; ++m) {
;                 const int row = row0 + ai * 128 + m * 16; const f32x4 p = pq[ai * 4 + m];
;                 float sq = (p[0] + p[1]) + (p[2] + p[3]); sq += bperm_f(ln ^ 16, sq); sq += bperm_f(ln ^ 32, sq);
;                 const float rs = rsqrtf(sq * (1.0f / DM) + EPS);
;                 bf16_t* rowp = O + (size_t)row * NIN + col0;
; #pragma unroll
;                 for (int bj = 0; bj < 2; ++bj) { const f32x4 v0 = acc[ai][bj][m][0] * rs, v1 = acc[ai][bj][m][1] * rs;
;                     u32x4 w; w.x = pk2(v0[0], v0[1]); w.y = pk2(v0[2], v0[3]); w.z = pk2(v1[0], v1[1]); w.w = pk2(v1[2], v1[3]);
;                     *(u32x4*)(rowp + bj * 128) = w; }
	v_pk_add_f32 v[108:109], v[108:109], v[112:113]
	ds_bpermute_b32 v113, v199, v109
	ds_bpermute_b32 v112, v199, v108
	s_waitcnt lgkmcnt(0)
	v_pk_add_f32 v[108:109], v[108:109], v[112:113]
	s_nop 0
	v_pk_fma_f32 v[108:109], v[108:109], s[42:43], v[188:189] op_sel_hi:[1,0,0]
	s_nop 0
	v_mul_f32_e32 v112, 0x4b800000, v109
	v_cmp_gt_f32_e64 s[40:41], s29, v109
	v_cmp_gt_f32_e32 vcc, s29, v108
	s_nop 0
	v_cndmask_b32_e64 v109, v109, v112, s[40:41]
	v_rsq_f32_e32 v109, v109
	s_nop 0
	v_mul_f32_e32 v112, 0x45800000, v109
	v_cndmask_b32_e64 v112, v109, v112, s[40:41]
	v_pk_mul_f32 v[98:99], v[98:99], v[112:113] op_sel_hi:[1,0]
	v_pk_mul_f32 v[96:97], v[96:97], v[112:113] op_sel_hi:[1,0]
	v_pk_mul_f32 v[114:115], v[94:95], v[112:113] op_sel_hi:[1,0]
	v_pk_mul_f32 v[94:95], v[92:93], v[112:113] op_sel_hi:[1,0]
	v_cvt_pk_bf16_f32 v92, v96, v97
	v_cvt_pk_bf16_f32 v93, v98, v99
	v_cvt_pk_bf16_f32 v94, v94, v95
	v_cvt_pk_bf16_f32 v95, v114, v115
	global_store_dwordx4 v[110:111], v[92:95], off
	v_pk_mul_f32 v[90:91], v[90:91], v[112:113] op_sel_hi:[1,0]
	v_pk_mul_f32 v[88:89], v[88:89], v[112:113] op_sel_hi:[1,0]
	v_pk_mul_f32 v[92:93], v[86:87], v[112:113] op_sel_hi:[1,0]
	v_pk_mul_f32 v[86:87], v[84:85], v[112:113] op_sel_hi:[1,0]
	v_cvt_pk_bf16_f32 v84, v88, v89
	v_cvt_pk_bf16_f32 v85, v90, v91
	v_cvt_pk_bf16_f32 v86, v86, v87
	v_cvt_pk_bf16_f32 v87, v92, v93
	global_store_dwordx4 v[110:111], v[84:87], off offset:256
	s_nop 1
	v_mul_f32_e32 v84, 0x4b800000, v108
	v_cndmask_b32_e32 v84, v108, v84, vcc
	v_rsq_f32_e32 v84, v84
	v_mad_i64_i32 v[86:87], s[40:41], v192, s72, v[180:181]
	v_lshl_add_u64 v[86:87], v[86:87], 0, v[182:183]
	v_mul_f32_e32 v85, 0x45800000, v84
	v_cndmask_b32_e32 v84, v84, v85, vcc
	v_pk_mul_f32 v[82:83], v[82:83], v[84:85] op_sel_hi:[1,0]
	v_pk_mul_f32 v[80:81], v[80:81], v[84:85] op_sel_hi:[1,0]
	v_pk_mul_f32 v[88:89], v[78:79], v[84:85] op_sel_hi:[1,0]
	v_pk_mul_f32 v[78:79], v[76:77], v[84:85] op_sel_hi:[1,0]
	v_cvt_pk_bf16_f32 v76, v80, v81
	v_cvt_pk_bf16_f32 v77, v82, v83
	v_cvt_pk_bf16_f32 v78, v78, v79
	v_cvt_pk_bf16_f32 v79, v88, v89
	global_store_dwordx4 v[86:87], v[76:79], off
	v_pk_mul_f32 v[74:75], v[74:75], v[84:85] op_sel_hi:[1,0]
	v_pk_mul_f32 v[72:73], v[72:73], v[84:85] op_sel_hi:[1,0]
	v_pk_mul_f32 v[76:77], v[70:71], v[84:85] op_sel_hi:[1,0]
	v_pk_mul_f32 v[70:71], v[68:69], v[84:85] op_sel_hi:[1,0]
	v_cvt_pk_bf16_f32 v68, v72, v73
	v_cvt_pk_bf16_f32 v69, v74, v75
	v_cvt_pk_bf16_f32 v70, v70, v71
	v_cvt_pk_bf16_f32 v71, v76, v77
	global_store_dwordx4 v[86:87], v[68:71], off offset:256
	v_mov_b32_e32 v72, v125
	v_mov_b32_e32 v73, v126
	v_mov_b32_e32 v68, v129
	v_mov_b32_e32 v69, v130
	v_mov_b32_e32 v129, v131
	v_mov_b32_e32 v125, v127
	v_pk_add_f32 v[68:69], v[68:69], v[128:129]
	v_pk_add_f32 v[72:73], v[72:73], v[124:125]
	v_mov_b32_e32 v75, v68
	v_mov_b32_e32 v74, v72
	v_mov_b32_e32 v68, v73
	v_pk_add_f32 v[68:69], v[74:75], v[68:69]
	ds_bpermute_b32 v73, v2, v69
	ds_bpermute_b32 v72, v2, v68
	v_mad_i64_i32 v[70:71], s[40:41], v190, s72, v[180:181]
	v_lshl_add_u64 v[70:71], v[70:71], 0, v[182:183]
	s_waitcnt lgkmcnt(0)
	v_pk_add_f32 v[68:69], v[68:69], v[72:73]
	ds_bpermute_b32 v73, v199, v69
	ds_bpermute_b32 v72, v199, v68
	s_waitcnt lgkmcnt(0)
; __device__ __forceinline__ unsigned pk2(float lo, float hi) { const f32x2_t v = {lo, hi}; const bf16x2_t b = __builtin_convertvector(v, bf16x2_t); return __builtin_bit_cast(unsigned, b); }
; __device__ __forceinline__ float bperm_f(int src_lane, float v) { return __builtin_bit_cast(float, __builtin_amdgcn_ds_bpermute(src_lane << 2, __builtin_bit_cast(int, v))); }
;     __device__ __forceinline__ void operator()(Acc& acc, const Unit& u, int wr, int wc, int fr, int fq) const {
;     ...
;         for (int ai = 0; ai < 2; ++ai)
; #pragma unroll
;             for (int m = 0; m < 4; ++m) {
;                 const int row = row0 + ai * 128 + m * 16; const f32x4 p = pq[ai * 4 + m];
;                 float sq = (p[0] + p[1]) + (p[2] + p[3]); sq += bperm_f(ln ^ 16, sq); sq += bperm_f(ln ^ 32, sq);
;                 const float rs = rsqrtf(sq * (1.0f / DM) + EPS);
;                 bf16_t* rowp = O + (size_t)row * NIN + col0;
; #pragma unroll
;                 for (int bj = 0; bj < 2; ++bj) { const f32x4 v0 = acc[ai][bj][m][0] * rs, v1 = acc[ai][bj][m][1] * rs;
;                     u32x4 w; w.x = pk2(v0[0], v0[1]); w.y = pk2(v0[2], v0[3]); w.z = pk2(v1[0], v1[1]); w.w = pk2(v1[2], v1[3]);
;                     *(u32x4*)(rowp + bj * 128) = w; }
	v_pk_add_f32 v[68:69], v[68:69], v[72:73]
	s_nop 0
	v_pk_fma_f32 v[68:69], v[68:69], s[42:43], v[188:189] op_sel_hi:[1,0,0]
	s_nop 0
	v_mul_f32_e32 v72, 0x4b800000, v69
	v_cmp_gt_f32_e64 s[40:41], s29, v69
	v_cmp_gt_f32_e32 vcc, s29, v68
	s_nop 0
	v_cndmask_b32_e64 v69, v69, v72, s[40:41]
	v_rsq_f32_e32 v69, v69
	s_nop 0
	v_mul_f32_e32 v72, 0x45800000, v69
	v_cndmask_b32_e64 v72, v69, v72, s[40:41]
	v_pk_mul_f32 v[66:67], v[66:67], v[72:73] op_sel_hi:[1,0]
	v_pk_mul_f32 v[64:65], v[64:65], v[72:73] op_sel_hi:[1,0]
	v_pk_mul_f32 v[74:75], v[62:63], v[72:73] op_sel_hi:[1,0]
	v_pk_mul_f32 v[62:63], v[60:61], v[72:73] op_sel_hi:[1,0]
	v_cvt_pk_bf16_f32 v60, v64, v65
	v_cvt_pk_bf16_f32 v61, v66, v67
	v_cvt_pk_bf16_f32 v62, v62, v63
	v_cvt_pk_bf16_f32 v63, v74, v75
	global_store_dwordx4 v[70:71], v[60:63], off
	v_pk_mul_f32 v[58:59], v[58:59], v[72:73] op_sel_hi:[1,0]
	v_pk_mul_f32 v[56:57], v[56:57], v[72:73] op_sel_hi:[1,0]
	v_pk_mul_f32 v[60:61], v[54:55], v[72:73] op_sel_hi:[1,0]
	v_pk_mul_f32 v[54:55], v[52:53], v[72:73] op_sel_hi:[1,0]
	v_cvt_pk_bf16_f32 v52, v56, v57
	v_cvt_pk_bf16_f32 v53, v58, v59
	v_cvt_pk_bf16_f32 v54, v54, v55
	v_cvt_pk_bf16_f32 v55, v60, v61
	global_store_dwordx4 v[70:71], v[52:55], off offset:256
	s_nop 1
	v_mul_f32_e32 v52, 0x4b800000, v68
	v_cndmask_b32_e32 v52, v68, v52, vcc
	v_rsq_f32_e32 v52, v52
	v_mad_i64_i32 v[54:55], s[40:41], v186, s72, v[180:181]
	v_lshl_add_u64 v[54:55], v[54:55], 0, v[182:183]
	v_mul_f32_e32 v53, 0x45800000, v52
	v_cndmask_b32_e32 v52, v52, v53, vcc
	v_pk_mul_f32 v[50:51], v[50:51], v[52:53] op_sel_hi:[1,0]
	v_pk_mul_f32 v[48:49], v[48:49], v[52:53] op_sel_hi:[1,0]
	v_pk_mul_f32 v[56:57], v[46:47], v[52:53] op_sel_hi:[1,0]
	v_pk_mul_f32 v[46:47], v[44:45], v[52:53] op_sel_hi:[1,0]
	v_cvt_pk_bf16_f32 v44, v48, v49
	v_cvt_pk_bf16_f32 v45, v50, v51
	v_cvt_pk_bf16_f32 v46, v46, v47
	v_cvt_pk_bf16_f32 v47, v56, v57
	global_store_dwordx4 v[54:55], v[44:47], off
	v_pk_mul_f32 v[42:43], v[42:43], v[52:53] op_sel_hi:[1,0]
	v_pk_mul_f32 v[40:41], v[40:41], v[52:53] op_sel_hi:[1,0]
	v_pk_mul_f32 v[44:45], v[38:39], v[52:53] op_sel_hi:[1,0]
	v_pk_mul_f32 v[38:39], v[36:37], v[52:53] op_sel_hi:[1,0]
	v_cvt_pk_bf16_f32 v36, v40, v41
	v_cvt_pk_bf16_f32 v37, v42, v43
	v_cvt_pk_bf16_f32 v38, v38, v39
	v_cvt_pk_bf16_f32 v39, v44, v45
	global_store_dwordx4 v[54:55], v[36:39], off offset:256
	v_mov_b32_e32 v40, v101
	v_mov_b32_e32 v41, v102
	v_mov_b32_e32 v36, v105
	v_mov_b32_e32 v37, v106
	v_mov_b32_e32 v105, v107
	v_mov_b32_e32 v101, v103
	v_pk_add_f32 v[36:37], v[36:37], v[104:105]
	v_pk_add_f32 v[40:41], v[40:41], v[100:101]
	v_mov_b32_e32 v43, v36
	v_mov_b32_e32 v42, v40
	v_mov_b32_e32 v36, v41
	v_pk_add_f32 v[36:37], v[42:43], v[36:37]
	ds_bpermute_b32 v41, v2, v37
	ds_bpermute_b32 v40, v2, v36
	v_mad_i64_i32 v[38:39], s[40:41], v184, s72, v[180:181]
	v_lshl_add_u64 v[38:39], v[38:39], 0, v[182:183]
	s_waitcnt lgkmcnt(0)
	v_pk_add_f32 v[36:37], v[36:37], v[40:41]
	ds_bpermute_b32 v41, v199, v37
	ds_bpermute_b32 v40, v199, v36
	s_waitcnt lgkmcnt(0)
	v_pk_add_f32 v[36:37], v[36:37], v[40:41]
	s_nop 0
	v_pk_fma_f32 v[36:37], v[36:37], s[42:43], v[188:189] op_sel_hi:[1,0,0]
	s_nop 0
	v_mul_f32_e32 v40, 0x4b800000, v37
	v_cmp_gt_f32_e64 s[40:41], s29, v37
	v_cmp_gt_f32_e32 vcc, s29, v36
	s_nop 0
	v_cndmask_b32_e64 v37, v37, v40, s[40:41]
	v_rsq_f32_e32 v37, v37
	s_nop 0
	v_mul_f32_e32 v40, 0x45800000, v37
	v_cndmask_b32_e64 v40, v37, v40, s[40:41]
	v_pk_mul_f32 v[34:35], v[34:35], v[40:41] op_sel_hi:[1,0]
	v_pk_mul_f32 v[32:33], v[32:33], v[40:41] op_sel_hi:[1,0]
	v_pk_mul_f32 v[42:43], v[30:31], v[40:41] op_sel_hi:[1,0]
	v_pk_mul_f32 v[30:31], v[28:29], v[40:41] op_sel_hi:[1,0]
	v_cvt_pk_bf16_f32 v28, v32, v33
	v_cvt_pk_bf16_f32 v29, v34, v35
	v_cvt_pk_bf16_f32 v30, v30, v31
	v_cvt_pk_bf16_f32 v31, v42, v43
	global_store_dwordx4 v[38:39], v[28:31], off
	v_pk_mul_f32 v[26:27], v[26:27], v[40:41] op_sel_hi:[1,0]
	v_pk_mul_f32 v[24:25], v[24:25], v[40:41] op_sel_hi:[1,0]
	v_pk_mul_f32 v[28:29], v[22:23], v[40:41] op_sel_hi:[1,0]
	v_pk_mul_f32 v[22:23], v[20:21], v[40:41] op_sel_hi:[1,0]
	v_cvt_pk_bf16_f32 v20, v24, v25
	v_cvt_pk_bf16_f32 v21, v26, v27
	v_cvt_pk_bf16_f32 v22, v22, v23
	v_cvt_pk_bf16_f32 v23, v28, v29
	global_store_dwordx4 v[38:39], v[20:23], off offset:256
	s_nop 1
	v_mul_f32_e32 v20, 0x4b800000, v36
	v_cndmask_b32_e32 v20, v36, v20, vcc
	v_rsq_f32_e32 v20, v20
	v_mad_i64_i32 v[22:23], s[40:41], v178, s72, v[180:181]
	v_lshl_add_u64 v[22:23], v[22:23], 0, v[182:183]
	v_mul_f32_e32 v21, 0x45800000, v20
	v_cndmask_b32_e32 v20, v20, v21, vcc
	v_pk_mul_f32 v[18:19], v[18:19], v[20:21] op_sel_hi:[1,0]
	v_pk_mul_f32 v[16:17], v[16:17], v[20:21] op_sel_hi:[1,0]
	v_pk_mul_f32 v[24:25], v[14:15], v[20:21] op_sel_hi:[1,0]
	v_pk_mul_f32 v[14:15], v[12:13], v[20:21] op_sel_hi:[1,0]
	v_cvt_pk_bf16_f32 v12, v16, v17
	v_cvt_pk_bf16_f32 v13, v18, v19
	v_cvt_pk_bf16_f32 v14, v14, v15
	v_cvt_pk_bf16_f32 v15, v24, v25
	global_store_dwordx4 v[22:23], v[12:15], off
	v_pk_mul_f32 v[10:11], v[10:11], v[20:21] op_sel_hi:[1,0]
	v_pk_mul_f32 v[8:9], v[8:9], v[20:21] op_sel_hi:[1,0]
	v_pk_mul_f32 v[12:13], v[6:7], v[20:21] op_sel_hi:[1,0]
	v_pk_mul_f32 v[6:7], v[4:5], v[20:21] op_sel_hi:[1,0]
	v_cvt_pk_bf16_f32 v4, v8, v9
	v_cvt_pk_bf16_f32 v5, v10, v11
	v_cvt_pk_bf16_f32 v6, v6, v7
	v_cvt_pk_bf16_f32 v7, v12, v13
	s_mov_b64 s[40:41], -1
	s_andn2_b64 vcc, exec, s[38:39]
	global_store_dwordx4 v[22:23], v[4:7], off offset:256
	s_cbranch_vccnz .LBB0_830
	s_andn2_b64 vcc, exec, s[4:5]
	s_cbranch_vccnz .LBB0_829
	s_barrier
	s_branch .LBB0_829
